# FFN-up phases: tail round units split into half units (rows) over 44 workgroups with a hand-written half epilogue
# baseline (speedup 1.0000x reference)
.LBB0_1468:
	v_readlane_b32 s0, v253, 0
	v_readlane_b32 s1, v253, 1
	s_cmp_lt_i32 s0, 8
	s_cselect_b64 s[0:1], -1, 0
	s_and_b64 s[6:7], s[0:1], s[6:7]
	v_readlane_b32 s8, v253, 35
	s_cmp_lt_i32 s8, 6
	s_mul_i32 s61, s8, 0x2c2
	s_cselect_b64 s[16:17], -1, 0
	s_add_i32 s61, s61, 6
	s_andn2_b64 vcc, exec, s[6:7]
	s_mul_i32 s62, s8, 0x2c3
	s_cbranch_vccnz .LBB0_1489
	s_mov_b64 s[6:7], s[92:93]
	v_mov_b32_e32 v8, v180
	s_cmpk_gt_i32 s94, 0x1615
	s_nop 0
	v_readfirstlane_b32 s21, v8
	s_cbranch_scc1 .LBB0_1489
	v_lshlrev_b32_e32 v0, 4, v8
	s_waitcnt lgkmcnt(0)
	v_add_u32_e32 v1, 0x2000, v0
	v_ashrrev_i32_e32 v2, 31, v1
	v_lshrrev_b32_e32 v2, 22, v2
	v_add_u32_e32 v2, v1, v2
	v_ashrrev_i32_e32 v9, 10, v2
	v_mul_i32_i24_e32 v2, 0x400, v9
	v_sub_u32_e32 v1, v1, v2
	v_lshrrev_b32_e32 v2, 4, v1
	v_bitop3_b32 v1, v2, v1, 32 bitop3:0x6c
	v_ashrrev_i32_e32 v2, 31, v1
	v_lshrrev_b32_e32 v2, 26, v2
	v_add_u32_e32 v2, v1, v2
	v_lshlrev_b32_e32 v3, 3, v9
	v_ashrrev_i32_e32 v10, 6, v2
	v_and_b32_e32 v3, -16, v3
	v_add_u32_e32 v3, v10, v3
	v_and_b32_e32 v4, 3, v10
	s_mov_b32 s8, 0x1fffe0
	v_lshrrev_b32_e32 v5, 2, v3
	v_lshlrev_b32_e32 v6, 1, v3
	v_and_b32_e32 v2, 0xc0, v2
	v_and_or_b32 v4, v3, s8, v4
	v_and_b32_e32 v5, 4, v5
	v_and_b32_e32 v6, 24, v6
	v_sub_u32_e32 v1, v1, v2
	v_mov_b32_e32 v2, 1
	v_or3_b32 v4, v4, v5, v6
	v_lshlrev_b32_e32 v5, 5, v9
	v_ashrrev_i16_sdwa v1, v2, sext(v1) dst_sel:DWORD dst_unused:UNUSED_PAD src0_sel:DWORD src1_sel:BYTE_0
	v_and_b32_e32 v5, 32, v5
	v_bfe_i32 v11, v1, 0, 16
	v_add_lshl_u32 v1, v5, v11, 1
	v_lshl_add_u32 v128, v4, 11, v1
	v_lshl_add_u32 v130, v3, 11, v1
	v_bfe_i32 v1, v8, 27, 1
	v_lshrrev_b32_e32 v1, 22, v1
	v_add_u32_e32 v1, v0, v1
	v_and_b32_e32 v1, 0xfffffc00, v1
	v_sub_u32_e32 v0, v0, v1
	v_lshrrev_b32_e32 v1, 4, v0
	s_load_dwordx2 s[6:7], s[6:7], 0x120
	v_bitop3_b32 v1, v1, v0, 32 bitop3:0x6c
	v_ashrrev_i32_e32 v0, 31, v0
	v_lshrrev_b32_e32 v0, 26, v0
	v_add_u32_e32 v0, v1, v0
	v_ashrrev_i32_e32 v12, 6, v0
	v_ashrrev_i32_e32 v0, 31, v8
	v_lshrrev_b32_e32 v0, 26, v0
	s_waitcnt lgkmcnt(0)
	s_add_u32 s38, s6, 0x2e10b200
	v_add_u32_e32 v0, v8, v0
	s_addc_u32 s39, s7, 0
	v_ashrrev_i32_e32 v13, 6, v0
	s_add_u32 s40, s6, 0x800000
	v_lshlrev_b32_e32 v0, 3, v13
	s_addc_u32 s41, s7, 0
	s_ashr_i32 s18, s21, 6
	v_and_b32_e32 v0, -16, v0
	s_ashr_i32 s19, s21, 8
	s_lshl_b32 s42, s18, 10
	v_add_u32_e32 v0, v12, v0
	v_and_b32_e32 v3, 3, v12
	v_and_or_b32 v3, v0, s8, v3
	s_and_b64 s[8:9], s[16:17], exec
	s_cselect_b32 s8, s62, s61
	v_readlane_b32 s9, v253, 34
	v_lshrrev_b32_e32 v4, 2, v0
	v_lshlrev_b32_e32 v5, 1, v0
	s_add_i32 s8, s8, s9
	v_and_b32_e32 v4, 4, v4
	v_and_b32_e32 v5, 24, v5
	s_mul_hi_i32 s9, s8, 0x2e8ba2e9
	v_or3_b32 v3, v3, v4, v5
	v_mul_i32_i24_e32 v5, 64, v12
	s_lshr_b32 s10, s9, 31
	s_ashr_i32 s9, s9, 5
	v_sub_u32_e32 v1, v1, v5
	s_add_i32 s9, s9, s10
	v_lshlrev_b32_e32 v4, 5, v13
	v_ashrrev_i16_sdwa v1, v2, sext(v1) dst_sel:DWORD dst_unused:UNUSED_PAD src0_sel:DWORD src1_sel:BYTE_0
	s_lshl_b32 s10, s9, 3
	v_and_b32_e32 v4, 32, v4
	v_bfe_i32 v14, v1, 0, 16
	s_sub_i32 s11, 0x101, s10
	v_add_lshl_u32 v1, v4, v14, 1
	s_min_u32 s11, s11, 8
	s_mulk_i32 s9, 0xb0
	v_lshl_add_u32 v132, v3, 11, v1
	s_sub_i32 s12, s8, s9
	v_cvt_f32_ubyte0_e32 v3, s11
	v_cvt_f32_i32_e32 v2, s12
	v_rcp_iflag_f32_e32 v4, v3
	v_lshl_add_u32 v134, v0, 11, v1
	s_ashr_i32 s8, s12, 30
	s_or_b32 s13, s8, 1
	v_mul_f32_e32 v0, v2, v4
	v_trunc_f32_e32 v0, v0
	v_fma_f32 v1, -v0, v3, v2
	v_cvt_i32_f32_e32 v0, v0
	v_cmp_ge_f32_e64 s[8:9], |v1|, v3
	s_and_b64 s[8:9], s[8:9], exec
	s_cselect_b32 s8, s13, 0
	v_readfirstlane_b32 s9, v0
	s_add_i32 s20, s9, s8
	s_mul_i32 s8, s20, s11
	s_sub_i32 s8, s12, s8
	s_sext_i32_i16 s8, s8
	s_add_i32 s8, s10, s8
	s_ashr_i32 s9, s8, 31
	s_bfe_i64 s[12:13], s[20:21], 0x100000
	s_lshl_b64 s[10:11], s[8:9], 19
	s_lshl_b64 s[12:13], s[12:13], 19
	s_add_u32 s34, s40, s12
	s_addc_u32 s35, s41, s13
	s_add_i32 s43, s42, 0
	s_add_i32 m0, s43, 0x10000
	v_mov_b32_e32 v133, 0
	global_load_lds_dwordx4 v132, s[34:35]
	s_add_i32 m0, s43, 0x12000
	s_add_u32 s12, s34, 0x40000
	global_load_lds_dwordx4 v128, s[34:35]
	s_addc_u32 s13, s35, 0
	s_add_i32 m0, s43, 0x14000
	v_mov_b32_e32 v129, v133
	global_load_lds_dwordx4 v132, s[12:13]
	s_add_i32 m0, s43, 0x16000
	s_add_u32 s30, s38, s10
	s_addc_u32 s31, s39, s11
	s_add_i32 s44, s43, 0x2000
	global_load_lds_dwordx4 v128, s[12:13]
	s_mov_b32 m0, s43
	s_add_u32 s10, s30, 0x40000
	global_load_lds_dwordx4 v134, s[30:31]
	s_mov_b32 m0, s44
	s_addc_u32 s11, s31, 0
	s_add_i32 s45, s43, 0x4000
	global_load_lds_dwordx4 v130, s[30:31]
	s_mov_b32 m0, s45
	s_add_i32 s48, s43, 0x6000
	global_load_lds_dwordx4 v134, s[10:11]
	s_mov_b32 m0, s48
	v_mov_b32_e32 v135, v133
	global_load_lds_dwordx4 v130, s[10:11]
	v_mov_b32_e32 v131, v133
	s_cmp_eq_u32 s19, 1
	s_mov_b32 s49, 0
	s_mov_b32 s101, 0xf
	s_mov_b32 s100, 0xf
	v_lshl_add_u64 v[6:7], s[34:35], 0, v[132:133]
	v_lshl_add_u64 v[4:5], s[34:35], 0, v[128:129]
	v_lshl_add_u64 v[0:1], s[30:31], 0, v[134:135]
	s_cselect_b64 s[10:11], -1, 0
	s_cmp_lg_u32 s19, 1
	v_lshl_add_u64 v[2:3], s[30:31], 0, v[130:131]
	s_cbranch_scc1 .LBB0_1472
	s_barrier

.LBB0_1474:
	s_mov_b32 s101, s100
	s_andn2_b64 vcc, exec, s[6:7]
	s_mov_b32 s9, s22
	s_mov_b32 s8, s24
	s_mov_b64 s[34:35], s[28:29]
	s_mov_b64 s[30:31], s[26:27]
	s_cbranch_vccz .LBB0_1488
.LBB0_1475:
	s_add_i32 s49, s49, 1
	s_mul_i32 s6, s49, s47
	s_mul_hi_u32 s7, s49, s46
	s_add_i32 s7, s7, s6
	s_mul_i32 s6, s49, s46
	s_add_u32 s26, s6, s94
	s_addc_u32 s27, s7, s95
	s_mov_b32 s100, 0xf
	s_cmp_eq_u32 s46, 0x100
	s_cbranch_scc0 .Lhs_done_7
	s_cmp_eq_u32 s49, 22
	s_cbranch_scc0 .Lhs_done_7
	s_mov_b32 s27, 0
	s_mov_b32 s26, 0x7fffffff
	s_cmp_lt_u32 s94, 44
	s_cbranch_scc0 .Lhs_done_7
	s_lshr_b32 s26, s94, 1
	s_add_i32 s26, s26, 0x1600
	s_mov_b32 s100, 0x43
	s_bitcmp1_b32 s94, 0
	s_cbranch_scc0 .Lhs_done_7
	s_mov_b32 s100, 0x6c
.Lhs_done_7:
	v_cmp_gt_i64_e32 vcc, s[26:27], v[142:143]
	v_cmp_lt_i64_e64 s[6:7], s[26:27], v[140:141]
	s_cbranch_vccnz .LBB0_1481
	s_ashr_i32 s22, s26, 31
	s_lshr_b32 s22, s22, 29
	s_add_i32 s24, s26, s22
	s_and_b32 s22, s24, -8
	s_sub_i32 s25, s26, s22
	s_cmp_gt_i32 s25, 5
	s_mov_b64 s[22:23], -1
	s_cbranch_scc0 .LBB0_1478
	s_mul_i32 s22, s25, 0x2c2
	s_add_i32 s26, s22, 6
	s_mov_b64 s[22:23], 0

.LBB0_1482:
	ds_read_b128 v[144:147], v155
	ds_read_b128 v[148:151], v155 offset:1024
	ds_read_b128 v[160:163], v155 offset:2048
	ds_read_b128 v[164:167], v155 offset:3072
	ds_read_b128 v[168:171], v156
	ds_read_b128 v[172:175], v156 offset:1024
	ds_read_b128 v[176:179], v156 offset:2048
	ds_read_b128 v[182:185], v156 offset:3072
	s_add_u32 s34, s30, 0xfffc0080
	s_addc_u32 s35, s31, -1
	s_cmp_eq_u32 s65, 12
	s_cselect_b32 s37, s25, s35
	s_cselect_b32 s36, s58, s34
	s_cselect_b32 s35, s23, s64
	s_cselect_b32 s34, s59, s63
	v_lshl_add_u64 v[152:153], s[30:31], 0, v[136:137]
	s_add_i32 m0, s43, 0xc000
	ds_read_b128 v[186:189], v157
	ds_read_b128 v[190:193], v157 offset:1024
	ds_read_b128 v[194:197], v157 offset:2048
	ds_read_b128 v[198:201], v157 offset:3072
	ds_read_b128 v[202:205], v157 offset:4096
	ds_read_b128 v[206:209], v157 offset:5120
	ds_read_b128 v[210:213], v157 offset:6144
	ds_read_b128 v[214:217], v157 offset:7168
	global_load_lds_dwordx4 v[152:153], off
	v_lshl_add_u64 v[152:153], s[30:31], 0, v[138:139]
	s_add_i32 m0, s43, 0xe000
	s_nop 0
	global_load_lds_dwordx4 v[152:153], off
	s_waitcnt vmcnt(8)
	s_waitcnt lgkmcnt(0)
	s_barrier
	s_setprio 1
	s_waitcnt lgkmcnt(0)
	s_bitcmp1_b32 s101, 0
	s_cbranch_scc0 .Lmf_7_0
	v_mfma_f32_16x16x32_bf16 v[124:127], v[144:147], v[186:189], v[124:127]
	v_mfma_f32_16x16x32_bf16 v[120:123], v[160:163], v[186:189], v[120:123]
	v_mfma_f32_16x16x32_bf16 v[108:111], v[144:147], v[194:197], v[108:111]
	v_mfma_f32_16x16x32_bf16 v[104:107], v[160:163], v[194:197], v[104:107]
	v_mfma_f32_16x16x32_bf16 v[92:95], v[144:147], v[202:205], v[92:95]
	v_mfma_f32_16x16x32_bf16 v[88:91], v[160:163], v[202:205], v[88:91]
	v_mfma_f32_16x16x32_bf16 v[76:79], v[144:147], v[210:213], v[76:79]
	v_mfma_f32_16x16x32_bf16 v[72:75], v[160:163], v[210:213], v[72:75]
	v_mfma_f32_16x16x32_bf16 v[124:127], v[148:151], v[190:193], v[124:127]
	v_mfma_f32_16x16x32_bf16 v[120:123], v[164:167], v[190:193], v[120:123]
	v_mfma_f32_16x16x32_bf16 v[108:111], v[148:151], v[198:201], v[108:111]
	v_mfma_f32_16x16x32_bf16 v[104:107], v[164:167], v[198:201], v[104:107]
	v_mfma_f32_16x16x32_bf16 v[92:95], v[148:151], v[206:209], v[92:95]
	v_mfma_f32_16x16x32_bf16 v[88:91], v[164:167], v[206:209], v[88:91]
	v_mfma_f32_16x16x32_bf16 v[76:79], v[148:151], v[214:217], v[76:79]
	v_mfma_f32_16x16x32_bf16 v[72:75], v[164:167], v[214:217], v[72:75]
.Lmf_7_0:
	s_setprio 0
	s_setprio 1
	s_bitcmp1_b32 s101, 1
	s_cbranch_scc0 .Lmf_7_1
	v_mfma_f32_16x16x32_bf16 v[116:119], v[168:171], v[186:189], v[116:119]
	v_mfma_f32_16x16x32_bf16 v[112:115], v[176:179], v[186:189], v[112:115]
	v_mfma_f32_16x16x32_bf16 v[100:103], v[168:171], v[194:197], v[100:103]
	v_mfma_f32_16x16x32_bf16 v[96:99], v[176:179], v[194:197], v[96:99]
	v_mfma_f32_16x16x32_bf16 v[84:87], v[168:171], v[202:205], v[84:87]
	v_mfma_f32_16x16x32_bf16 v[80:83], v[176:179], v[202:205], v[80:83]
	v_mfma_f32_16x16x32_bf16 v[68:71], v[168:171], v[210:213], v[68:71]
	v_mfma_f32_16x16x32_bf16 v[64:67], v[176:179], v[210:213], v[64:67]
	v_mfma_f32_16x16x32_bf16 v[116:119], v[172:175], v[190:193], v[116:119]
	v_mfma_f32_16x16x32_bf16 v[112:115], v[182:185], v[190:193], v[112:115]
	v_mfma_f32_16x16x32_bf16 v[100:103], v[172:175], v[198:201], v[100:103]
	v_mfma_f32_16x16x32_bf16 v[96:99], v[182:185], v[198:201], v[96:99]
	v_mfma_f32_16x16x32_bf16 v[84:87], v[172:175], v[206:209], v[84:87]
	v_mfma_f32_16x16x32_bf16 v[80:83], v[182:185], v[206:209], v[80:83]
	v_mfma_f32_16x16x32_bf16 v[68:71], v[172:175], v[214:217], v[68:71]
	v_mfma_f32_16x16x32_bf16 v[64:67], v[182:185], v[214:217], v[64:67]
.Lmf_7_1:
	s_setprio 0
	s_barrier
	s_add_i32 s66, s54, s42
	v_lshl_add_u64 v[152:153], s[34:35], 0, v[132:133]
	s_mov_b32 m0, s66
	ds_read_b128 v[186:189], v157 offset:16384
	ds_read_b128 v[190:193], v157 offset:17408
	ds_read_b128 v[194:197], v157 offset:18432
	ds_read_b128 v[198:201], v157 offset:19456
	ds_read_b128 v[202:205], v157 offset:20480
	ds_read_b128 v[206:209], v157 offset:21504
	ds_read_b128 v[210:213], v157 offset:22528
	ds_read_b128 v[214:217], v157 offset:23552
	global_load_lds_dwordx4 v[152:153], off
	s_add_i32 m0, s66, 0x2000
	s_add_u32 s66, s34, 0x40000
	v_lshl_add_u64 v[218:219], s[34:35], 0, v[128:129]
	s_addc_u32 s67, s35, 0
	s_add_i32 s68, s55, s42
	global_load_lds_dwordx4 v[218:219], off
	v_lshl_add_u64 v[220:221], s[66:67], 0, v[132:133]
	s_mov_b32 m0, s68
	v_lshl_add_u64 v[222:223], s[36:37], 0, v[130:131]
	global_load_lds_dwordx4 v[220:221], off
	v_lshl_add_u64 v[220:221], s[66:67], 0, v[128:129]
	s_add_i32 m0, s68, 0x2000
	s_nop 0
	global_load_lds_dwordx4 v[220:221], off
	v_lshl_add_u64 v[220:221], s[36:37], 0, v[134:135]
	s_mov_b32 m0, s43
	s_nop 0
	global_load_lds_dwordx4 v[220:221], off
	s_mov_b32 m0, s44
	s_nop 0
	global_load_lds_dwordx4 v[222:223], off
	s_waitcnt vmcnt(8)
	s_waitcnt lgkmcnt(0)
	s_barrier
	s_setprio 1
	s_waitcnt lgkmcnt(0)
	s_bitcmp1_b32 s101, 2
	s_cbranch_scc0 .Lmf_7_2
	v_mfma_f32_16x16x32_bf16 v[60:63], v[144:147], v[186:189], v[60:63]
	v_mfma_f32_16x16x32_bf16 v[56:59], v[160:163], v[186:189], v[56:59]
	v_mfma_f32_16x16x32_bf16 v[44:47], v[144:147], v[194:197], v[44:47]
	v_mfma_f32_16x16x32_bf16 v[40:43], v[160:163], v[194:197], v[40:43]
	v_mfma_f32_16x16x32_bf16 v[28:31], v[144:147], v[202:205], v[28:31]
	v_mfma_f32_16x16x32_bf16 v[24:27], v[160:163], v[202:205], v[24:27]
	v_mfma_f32_16x16x32_bf16 v[12:15], v[144:147], v[210:213], v[12:15]
	v_mfma_f32_16x16x32_bf16 v[8:11], v[160:163], v[210:213], v[8:11]
	v_mfma_f32_16x16x32_bf16 v[60:63], v[148:151], v[190:193], v[60:63]
	v_mfma_f32_16x16x32_bf16 v[56:59], v[164:167], v[190:193], v[56:59]
	v_mfma_f32_16x16x32_bf16 v[44:47], v[148:151], v[198:201], v[44:47]
	v_mfma_f32_16x16x32_bf16 v[40:43], v[164:167], v[198:201], v[40:43]
	v_mfma_f32_16x16x32_bf16 v[28:31], v[148:151], v[206:209], v[28:31]
	v_mfma_f32_16x16x32_bf16 v[24:27], v[164:167], v[206:209], v[24:27]
	v_mfma_f32_16x16x32_bf16 v[12:15], v[148:151], v[214:217], v[12:15]
	v_mfma_f32_16x16x32_bf16 v[8:11], v[164:167], v[214:217], v[8:11]
.Lmf_7_2:
	s_setprio 0
	s_setprio 1
	s_bitcmp1_b32 s101, 3
	s_cbranch_scc0 .Lmf_7_3
	v_mfma_f32_16x16x32_bf16 v[52:55], v[168:171], v[186:189], v[52:55]
	v_mfma_f32_16x16x32_bf16 v[48:51], v[176:179], v[186:189], v[48:51]
	v_mfma_f32_16x16x32_bf16 v[36:39], v[168:171], v[194:197], v[36:39]
	v_mfma_f32_16x16x32_bf16 v[32:35], v[176:179], v[194:197], v[32:35]
	v_mfma_f32_16x16x32_bf16 v[20:23], v[168:171], v[202:205], v[20:23]
	v_mfma_f32_16x16x32_bf16 v[16:19], v[176:179], v[202:205], v[16:19]
	v_mfma_f32_16x16x32_bf16 v[4:7], v[168:171], v[210:213], v[4:7]
	v_mfma_f32_16x16x32_bf16 v[0:3], v[176:179], v[210:213], v[0:3]
	v_mfma_f32_16x16x32_bf16 v[52:55], v[172:175], v[190:193], v[52:55]
	v_mfma_f32_16x16x32_bf16 v[48:51], v[182:185], v[190:193], v[48:51]
	v_mfma_f32_16x16x32_bf16 v[36:39], v[172:175], v[198:201], v[36:39]
	v_mfma_f32_16x16x32_bf16 v[32:35], v[182:185], v[198:201], v[32:35]
	v_mfma_f32_16x16x32_bf16 v[20:23], v[172:175], v[206:209], v[20:23]
	v_mfma_f32_16x16x32_bf16 v[16:19], v[182:185], v[206:209], v[16:19]
	v_mfma_f32_16x16x32_bf16 v[4:7], v[172:175], v[214:217], v[4:7]
	v_mfma_f32_16x16x32_bf16 v[0:3], v[182:185], v[214:217], v[0:3]
.Lmf_7_3:
	s_setprio 0
	s_barrier
	s_add_i32 s66, 0, 0x18000
	v_add_u32_e32 v159, s66, v154
	s_add_i32 s67, 0, 0x1c000
	ds_read_b128 v[144:147], v159
	ds_read_b128 v[148:151], v159 offset:1024
	ds_read_b128 v[160:163], v159 offset:2048
	ds_read_b128 v[164:167], v159 offset:3072
	v_add_u32_e32 v159, s67, v154
	ds_read_b128 v[168:171], v159
	ds_read_b128 v[172:175], v159 offset:1024
	ds_read_b128 v[176:179], v159 offset:2048
	ds_read_b128 v[182:185], v159 offset:3072
	s_add_u32 s36, s36, 0x40000
	s_addc_u32 s37, s37, 0
	s_mov_b32 m0, s45
	v_lshl_add_u64 v[224:225], s[36:37], 0, v[134:135]
	ds_read_b128 v[186:189], v157 offset:32768
	ds_read_b128 v[190:193], v157 offset:33792
	ds_read_b128 v[194:197], v157 offset:34816
	ds_read_b128 v[198:201], v157 offset:35840
	ds_read_b128 v[202:205], v157 offset:36864
	ds_read_b128 v[206:209], v157 offset:37888
	ds_read_b128 v[210:213], v157 offset:38912
	ds_read_b128 v[214:217], v157 offset:39936
	global_load_lds_dwordx4 v[224:225], off
	v_lshl_add_u64 v[224:225], s[36:37], 0, v[130:131]
	s_mov_b32 m0, s48
	s_nop 0
	global_load_lds_dwordx4 v[224:225], off
	s_waitcnt vmcnt(8)
	s_waitcnt lgkmcnt(0)
	s_barrier
	s_setprio 1
	s_waitcnt lgkmcnt(0)
	s_bitcmp1_b32 s101, 0
	s_cbranch_scc0 .Lmf_7_4
	v_mfma_f32_16x16x32_bf16 v[124:127], v[144:147], v[186:189], v[124:127]
	v_mfma_f32_16x16x32_bf16 v[120:123], v[160:163], v[186:189], v[120:123]
	v_mfma_f32_16x16x32_bf16 v[108:111], v[144:147], v[194:197], v[108:111]
	v_mfma_f32_16x16x32_bf16 v[104:107], v[160:163], v[194:197], v[104:107]
	v_mfma_f32_16x16x32_bf16 v[92:95], v[144:147], v[202:205], v[92:95]
	v_mfma_f32_16x16x32_bf16 v[88:91], v[160:163], v[202:205], v[88:91]
	v_mfma_f32_16x16x32_bf16 v[76:79], v[144:147], v[210:213], v[76:79]
	v_mfma_f32_16x16x32_bf16 v[72:75], v[160:163], v[210:213], v[72:75]
	v_mfma_f32_16x16x32_bf16 v[124:127], v[148:151], v[190:193], v[124:127]
	v_mfma_f32_16x16x32_bf16 v[120:123], v[164:167], v[190:193], v[120:123]
	v_mfma_f32_16x16x32_bf16 v[108:111], v[148:151], v[198:201], v[108:111]
	v_mfma_f32_16x16x32_bf16 v[104:107], v[164:167], v[198:201], v[104:107]
	v_mfma_f32_16x16x32_bf16 v[92:95], v[148:151], v[206:209], v[92:95]
	v_mfma_f32_16x16x32_bf16 v[88:91], v[164:167], v[206:209], v[88:91]
	v_mfma_f32_16x16x32_bf16 v[76:79], v[148:151], v[214:217], v[76:79]
	v_mfma_f32_16x16x32_bf16 v[72:75], v[164:167], v[214:217], v[72:75]

.Lmf_7_5:
	s_setprio 0
	s_barrier
	s_add_i32 s36, s66, s42
	v_lshl_add_u64 v[152:153], v[152:153], 0, s[18:19]
	s_mov_b32 m0, s36
	ds_read_b128 v[186:189], v157 offset:49152
	ds_read_b128 v[190:193], v157 offset:50176
	ds_read_b128 v[194:197], v157 offset:51200
	ds_read_b128 v[198:201], v157 offset:52224
	ds_read_b128 v[202:205], v157 offset:53248
	ds_read_b128 v[206:209], v157 offset:54272
	ds_read_b128 v[210:213], v157 offset:55296
	ds_read_b128 v[214:217], v157 offset:56320
	global_load_lds_dwordx4 v[152:153], off
	s_add_i32 m0, s36, 0x2000
	s_add_u32 s34, s34, 0x40080
	v_lshl_add_u64 v[152:153], v[218:219], 0, s[18:19]
	s_addc_u32 s35, s35, 0
	s_add_i32 s36, s67, s42
	global_load_lds_dwordx4 v[152:153], off
	v_lshl_add_u64 v[152:153], s[34:35], 0, v[132:133]
	s_mov_b32 m0, s36
	s_nop 0
	global_load_lds_dwordx4 v[152:153], off
	v_lshl_add_u64 v[152:153], s[34:35], 0, v[128:129]
	s_add_i32 m0, s36, 0x2000
	s_nop 0
	global_load_lds_dwordx4 v[152:153], off
	v_lshl_add_u64 v[152:153], v[220:221], 0, s[18:19]
	s_mov_b32 m0, s52
	s_nop 0
	global_load_lds_dwordx4 v[152:153], off
	v_lshl_add_u64 v[152:153], v[222:223], 0, s[18:19]
	s_mov_b32 m0, s53
	s_nop 0
	global_load_lds_dwordx4 v[152:153], off
	s_waitcnt vmcnt(8)
	s_waitcnt lgkmcnt(0)
	s_barrier
	s_setprio 1
	s_waitcnt lgkmcnt(0)
	s_bitcmp1_b32 s101, 2
	s_cbranch_scc0 .Lmf_7_6
	v_mfma_f32_16x16x32_bf16 v[60:63], v[144:147], v[186:189], v[60:63]
	v_mfma_f32_16x16x32_bf16 v[56:59], v[160:163], v[186:189], v[56:59]
	v_mfma_f32_16x16x32_bf16 v[44:47], v[144:147], v[194:197], v[44:47]
	v_mfma_f32_16x16x32_bf16 v[40:43], v[160:163], v[194:197], v[40:43]
	v_mfma_f32_16x16x32_bf16 v[28:31], v[144:147], v[202:205], v[28:31]
	v_mfma_f32_16x16x32_bf16 v[24:27], v[160:163], v[202:205], v[24:27]
	v_mfma_f32_16x16x32_bf16 v[12:15], v[144:147], v[210:213], v[12:15]
	v_mfma_f32_16x16x32_bf16 v[8:11], v[160:163], v[210:213], v[8:11]
	v_mfma_f32_16x16x32_bf16 v[60:63], v[148:151], v[190:193], v[60:63]
	v_mfma_f32_16x16x32_bf16 v[56:59], v[164:167], v[190:193], v[56:59]
	v_mfma_f32_16x16x32_bf16 v[44:47], v[148:151], v[198:201], v[44:47]
	v_mfma_f32_16x16x32_bf16 v[40:43], v[164:167], v[198:201], v[40:43]
	v_mfma_f32_16x16x32_bf16 v[28:31], v[148:151], v[206:209], v[28:31]
	v_mfma_f32_16x16x32_bf16 v[24:27], v[164:167], v[206:209], v[24:27]
	v_mfma_f32_16x16x32_bf16 v[12:15], v[148:151], v[214:217], v[12:15]
	v_mfma_f32_16x16x32_bf16 v[8:11], v[164:167], v[214:217], v[8:11]

.Lmf_7_7:
	s_setprio 0
	s_barrier
	s_add_i32 s65, s65, 2
	s_add_u32 s30, s30, 0x100
	s_addc_u32 s31, s31, 0
	s_add_u32 s63, s63, 0x100
	s_addc_u32 s64, s64, 0
	s_cmp_gt_u32 s65, 13
	s_cbranch_scc0 .LBB0_1482
	s_and_b64 vcc, exec, s[20:21]
	s_cbranch_vccz .LBB0_1485
	s_barrier
.LBB0_1485:
	s_bitcmp1_b32 s101, 6
	s_cbranch_scc0 .Lff_full_7
	s_bitcmp1_b32 s101, 5
	s_cbranch_scc1 .Lff_h1_7
	v_and_b32_e32 v144, 15, v180
	v_bfe_u32 v145, v180, 4, 2
	s_lshl_b32 s98, s8, 8
	s_add_i32 s98, s98, s50
	v_add_u32_e32 v146, s98, v144
	v_lshlrev_b32_e32 v147, 2, v146
	s_lshl_b32 s98, s9, 7
	s_add_i32 s98, s98, s51
	v_lshl_add_u32 v148, v145, 3, s98
	v_mul_u32_u24_e32 v149, 0x1600, v146
	v_lshl_add_u32 v149, v148, 1, v149
	global_load_dword v160, v147, s[12:13] offset:0
	global_load_dword v161, v147, s[12:13] offset:64
	global_load_dword v162, v147, s[12:13] offset:128
	global_load_dword v163, v147, s[12:13] offset:192
	v_mov_b32_e32 v151, 0x358637bd
	v_mov_b32_e32 v152, 0xbfb8aa3b
	v_mov_b32_e32 v153, 0xbfb8aa3b
	v_mov_b32_e32 v158, 1.0
	v_mov_b32_e32 v159, 1.0
	s_waitcnt vmcnt(0)
	v_fmamk_f32 v150, v160, 0x3a800000, v151
	v_rsq_f32_e32 v150, v150
	s_nop 0
	v_pk_mul_f32 v[124:125], v[124:125], v[150:151] op_sel_hi:[1,0]
	v_pk_mul_f32 v[126:127], v[126:127], v[150:151] op_sel_hi:[1,0]
	v_pk_mul_f32 v[116:117], v[116:117], v[150:151] op_sel_hi:[1,0]
	v_pk_mul_f32 v[118:119], v[118:119], v[150:151] op_sel_hi:[1,0]
	v_pk_mul_f32 v[168:169], v[124:125], v[152:153]
	v_pk_mul_f32 v[170:171], v[126:127], v[152:153]
	v_exp_f32_e32 v168, v168
	v_exp_f32_e32 v169, v169
	v_exp_f32_e32 v170, v170
	v_exp_f32_e32 v171, v171
	v_pk_add_f32 v[168:169], v[168:169], v[158:159]
	v_pk_add_f32 v[170:171], v[170:171], v[158:159]
	v_rcp_f32_e32 v168, v168
	v_rcp_f32_e32 v169, v169
	v_rcp_f32_e32 v170, v170
	v_rcp_f32_e32 v171, v171
	v_pk_mul_f32 v[116:117], v[116:117], v[124:125]
	v_pk_mul_f32 v[118:119], v[118:119], v[126:127]
	v_pk_mul_f32 v[116:117], v[116:117], v[168:169]
	v_pk_mul_f32 v[118:119], v[118:119], v[170:171]
	v_pk_mul_f32 v[120:121], v[120:121], v[150:151] op_sel_hi:[1,0]
	v_pk_mul_f32 v[122:123], v[122:123], v[150:151] op_sel_hi:[1,0]
	v_pk_mul_f32 v[112:113], v[112:113], v[150:151] op_sel_hi:[1,0]
	v_pk_mul_f32 v[114:115], v[114:115], v[150:151] op_sel_hi:[1,0]
	v_pk_mul_f32 v[168:169], v[120:121], v[152:153]
	v_pk_mul_f32 v[170:171], v[122:123], v[152:153]
	v_exp_f32_e32 v168, v168
	v_exp_f32_e32 v169, v169
	v_exp_f32_e32 v170, v170
	v_exp_f32_e32 v171, v171
	v_pk_add_f32 v[168:169], v[168:169], v[158:159]
	v_pk_add_f32 v[170:171], v[170:171], v[158:159]
	v_rcp_f32_e32 v168, v168
	v_rcp_f32_e32 v169, v169
	v_rcp_f32_e32 v170, v170
	v_rcp_f32_e32 v171, v171
	v_pk_mul_f32 v[112:113], v[112:113], v[120:121]
	v_pk_mul_f32 v[114:115], v[114:115], v[122:123]
	v_pk_mul_f32 v[112:113], v[112:113], v[168:169]
	v_pk_mul_f32 v[114:115], v[114:115], v[170:171]
	v_cvt_pk_bf16_f32 v164, v116, v117
	v_cvt_pk_bf16_f32 v165, v118, v119
	v_cvt_pk_bf16_f32 v166, v112, v113
	v_cvt_pk_bf16_f32 v167, v114, v115
	global_store_dwordx4 v149, v[164:167], s[14:15]
	s_nop 1
	v_add_u32_e32 v149, 0x16000, v149
	v_fmamk_f32 v150, v161, 0x3a800000, v151
	v_rsq_f32_e32 v150, v150
	s_nop 0
	v_pk_mul_f32 v[108:109], v[108:109], v[150:151] op_sel_hi:[1,0]
	v_pk_mul_f32 v[110:111], v[110:111], v[150:151] op_sel_hi:[1,0]
	v_pk_mul_f32 v[100:101], v[100:101], v[150:151] op_sel_hi:[1,0]
	v_pk_mul_f32 v[102:103], v[102:103], v[150:151] op_sel_hi:[1,0]
	v_pk_mul_f32 v[168:169], v[108:109], v[152:153]
	v_pk_mul_f32 v[170:171], v[110:111], v[152:153]
	v_exp_f32_e32 v168, v168
	v_exp_f32_e32 v169, v169
	v_exp_f32_e32 v170, v170
	v_exp_f32_e32 v171, v171
	v_pk_add_f32 v[168:169], v[168:169], v[158:159]
	v_pk_add_f32 v[170:171], v[170:171], v[158:159]
	v_rcp_f32_e32 v168, v168
	v_rcp_f32_e32 v169, v169
	v_rcp_f32_e32 v170, v170
	v_rcp_f32_e32 v171, v171
	v_pk_mul_f32 v[100:101], v[100:101], v[108:109]
	v_pk_mul_f32 v[102:103], v[102:103], v[110:111]
	v_pk_mul_f32 v[100:101], v[100:101], v[168:169]
	v_pk_mul_f32 v[102:103], v[102:103], v[170:171]
	v_pk_mul_f32 v[104:105], v[104:105], v[150:151] op_sel_hi:[1,0]
	v_pk_mul_f32 v[106:107], v[106:107], v[150:151] op_sel_hi:[1,0]
	v_pk_mul_f32 v[96:97], v[96:97], v[150:151] op_sel_hi:[1,0]
	v_pk_mul_f32 v[98:99], v[98:99], v[150:151] op_sel_hi:[1,0]
	v_pk_mul_f32 v[168:169], v[104:105], v[152:153]
	v_pk_mul_f32 v[170:171], v[106:107], v[152:153]
	v_exp_f32_e32 v168, v168
	v_exp_f32_e32 v169, v169
	v_exp_f32_e32 v170, v170
	v_exp_f32_e32 v171, v171
	v_pk_add_f32 v[168:169], v[168:169], v[158:159]
	v_pk_add_f32 v[170:171], v[170:171], v[158:159]
	v_rcp_f32_e32 v168, v168
	v_rcp_f32_e32 v169, v169
	v_rcp_f32_e32 v170, v170
	v_rcp_f32_e32 v171, v171
	v_pk_mul_f32 v[96:97], v[96:97], v[104:105]
	v_pk_mul_f32 v[98:99], v[98:99], v[106:107]
	v_pk_mul_f32 v[96:97], v[96:97], v[168:169]
	v_pk_mul_f32 v[98:99], v[98:99], v[170:171]
	v_cvt_pk_bf16_f32 v164, v100, v101
	v_cvt_pk_bf16_f32 v165, v102, v103
	v_cvt_pk_bf16_f32 v166, v96, v97
	v_cvt_pk_bf16_f32 v167, v98, v99
	global_store_dwordx4 v149, v[164:167], s[14:15]
	s_nop 1
	v_add_u32_e32 v149, 0x16000, v149
	v_fmamk_f32 v150, v162, 0x3a800000, v151
	v_rsq_f32_e32 v150, v150
	s_nop 0
	v_pk_mul_f32 v[92:93], v[92:93], v[150:151] op_sel_hi:[1,0]
	v_pk_mul_f32 v[94:95], v[94:95], v[150:151] op_sel_hi:[1,0]
	v_pk_mul_f32 v[84:85], v[84:85], v[150:151] op_sel_hi:[1,0]
	v_pk_mul_f32 v[86:87], v[86:87], v[150:151] op_sel_hi:[1,0]
	v_pk_mul_f32 v[168:169], v[92:93], v[152:153]
	v_pk_mul_f32 v[170:171], v[94:95], v[152:153]
	v_exp_f32_e32 v168, v168
	v_exp_f32_e32 v169, v169
	v_exp_f32_e32 v170, v170
	v_exp_f32_e32 v171, v171
	v_pk_add_f32 v[168:169], v[168:169], v[158:159]
	v_pk_add_f32 v[170:171], v[170:171], v[158:159]
	v_rcp_f32_e32 v168, v168
	v_rcp_f32_e32 v169, v169
	v_rcp_f32_e32 v170, v170
	v_rcp_f32_e32 v171, v171
	v_pk_mul_f32 v[84:85], v[84:85], v[92:93]
	v_pk_mul_f32 v[86:87], v[86:87], v[94:95]
	v_pk_mul_f32 v[84:85], v[84:85], v[168:169]
	v_pk_mul_f32 v[86:87], v[86:87], v[170:171]
	v_pk_mul_f32 v[88:89], v[88:89], v[150:151] op_sel_hi:[1,0]
	v_pk_mul_f32 v[90:91], v[90:91], v[150:151] op_sel_hi:[1,0]
	v_pk_mul_f32 v[80:81], v[80:81], v[150:151] op_sel_hi:[1,0]
	v_pk_mul_f32 v[82:83], v[82:83], v[150:151] op_sel_hi:[1,0]
	v_pk_mul_f32 v[168:169], v[88:89], v[152:153]
	v_pk_mul_f32 v[170:171], v[90:91], v[152:153]
	v_exp_f32_e32 v168, v168
	v_exp_f32_e32 v169, v169
	v_exp_f32_e32 v170, v170
	v_exp_f32_e32 v171, v171
	v_pk_add_f32 v[168:169], v[168:169], v[158:159]
	v_pk_add_f32 v[170:171], v[170:171], v[158:159]
	v_rcp_f32_e32 v168, v168
	v_rcp_f32_e32 v169, v169
	v_rcp_f32_e32 v170, v170
	v_rcp_f32_e32 v171, v171
	v_pk_mul_f32 v[80:81], v[80:81], v[88:89]
	v_pk_mul_f32 v[82:83], v[82:83], v[90:91]
	v_pk_mul_f32 v[80:81], v[80:81], v[168:169]
	v_pk_mul_f32 v[82:83], v[82:83], v[170:171]
	v_cvt_pk_bf16_f32 v164, v84, v85
	v_cvt_pk_bf16_f32 v165, v86, v87
	v_cvt_pk_bf16_f32 v166, v80, v81
	v_cvt_pk_bf16_f32 v167, v82, v83
	global_store_dwordx4 v149, v[164:167], s[14:15]
	s_nop 1
	v_add_u32_e32 v149, 0x16000, v149
	v_fmamk_f32 v150, v163, 0x3a800000, v151
	v_rsq_f32_e32 v150, v150
	s_nop 0
	v_pk_mul_f32 v[76:77], v[76:77], v[150:151] op_sel_hi:[1,0]
	v_pk_mul_f32 v[78:79], v[78:79], v[150:151] op_sel_hi:[1,0]
	v_pk_mul_f32 v[68:69], v[68:69], v[150:151] op_sel_hi:[1,0]
	v_pk_mul_f32 v[70:71], v[70:71], v[150:151] op_sel_hi:[1,0]
	v_pk_mul_f32 v[168:169], v[76:77], v[152:153]
	v_pk_mul_f32 v[170:171], v[78:79], v[152:153]
	v_exp_f32_e32 v168, v168
	v_exp_f32_e32 v169, v169
	v_exp_f32_e32 v170, v170
	v_exp_f32_e32 v171, v171
	v_pk_add_f32 v[168:169], v[168:169], v[158:159]
	v_pk_add_f32 v[170:171], v[170:171], v[158:159]
	v_rcp_f32_e32 v168, v168
	v_rcp_f32_e32 v169, v169
	v_rcp_f32_e32 v170, v170
	v_rcp_f32_e32 v171, v171
	v_pk_mul_f32 v[68:69], v[68:69], v[76:77]
	v_pk_mul_f32 v[70:71], v[70:71], v[78:79]
	v_pk_mul_f32 v[68:69], v[68:69], v[168:169]
	v_pk_mul_f32 v[70:71], v[70:71], v[170:171]
	v_pk_mul_f32 v[72:73], v[72:73], v[150:151] op_sel_hi:[1,0]
	v_pk_mul_f32 v[74:75], v[74:75], v[150:151] op_sel_hi:[1,0]
	v_pk_mul_f32 v[64:65], v[64:65], v[150:151] op_sel_hi:[1,0]
	v_pk_mul_f32 v[66:67], v[66:67], v[150:151] op_sel_hi:[1,0]
	v_pk_mul_f32 v[168:169], v[72:73], v[152:153]
	v_pk_mul_f32 v[170:171], v[74:75], v[152:153]
	v_exp_f32_e32 v168, v168
	v_exp_f32_e32 v169, v169
	v_exp_f32_e32 v170, v170
	v_exp_f32_e32 v171, v171
	v_pk_add_f32 v[168:169], v[168:169], v[158:159]
	v_pk_add_f32 v[170:171], v[170:171], v[158:159]
	v_rcp_f32_e32 v168, v168
	v_rcp_f32_e32 v169, v169
	v_rcp_f32_e32 v170, v170
	v_rcp_f32_e32 v171, v171
	v_pk_mul_f32 v[64:65], v[64:65], v[72:73]
	v_pk_mul_f32 v[66:67], v[66:67], v[74:75]
	v_pk_mul_f32 v[64:65], v[64:65], v[168:169]
	v_pk_mul_f32 v[66:67], v[66:67], v[170:171]
	v_cvt_pk_bf16_f32 v164, v68, v69
	v_cvt_pk_bf16_f32 v165, v70, v71
	v_cvt_pk_bf16_f32 v166, v64, v65
	v_cvt_pk_bf16_f32 v167, v66, v67
	global_store_dwordx4 v149, v[164:167], s[14:15]
	s_branch .Lff_hend_7
.Lff_h1_7:
	v_and_b32_e32 v144, 15, v180
	v_bfe_u32 v145, v180, 4, 2
	s_lshl_b32 s98, s8, 8
	s_add_i32 s98, s98, s50
	s_add_i32 s98, s98, 0x80
	v_add_u32_e32 v146, s98, v144
	v_lshlrev_b32_e32 v147, 2, v146
	s_lshl_b32 s98, s9, 7
	s_add_i32 s98, s98, s51
	v_lshl_add_u32 v148, v145, 3, s98
	v_mul_u32_u24_e32 v149, 0x1600, v146
	v_lshl_add_u32 v149, v148, 1, v149
	global_load_dword v160, v147, s[12:13] offset:0
	global_load_dword v161, v147, s[12:13] offset:64
	global_load_dword v162, v147, s[12:13] offset:128
	global_load_dword v163, v147, s[12:13] offset:192
	v_mov_b32_e32 v151, 0x358637bd
	v_mov_b32_e32 v152, 0xbfb8aa3b
	v_mov_b32_e32 v153, 0xbfb8aa3b
	v_mov_b32_e32 v158, 1.0
	v_mov_b32_e32 v159, 1.0
	s_waitcnt vmcnt(0)
	v_fmamk_f32 v150, v160, 0x3a800000, v151
	v_rsq_f32_e32 v150, v150
	s_nop 0
	v_pk_mul_f32 v[60:61], v[60:61], v[150:151] op_sel_hi:[1,0]
	v_pk_mul_f32 v[62:63], v[62:63], v[150:151] op_sel_hi:[1,0]
	v_pk_mul_f32 v[52:53], v[52:53], v[150:151] op_sel_hi:[1,0]
	v_pk_mul_f32 v[54:55], v[54:55], v[150:151] op_sel_hi:[1,0]
	v_pk_mul_f32 v[168:169], v[60:61], v[152:153]
	v_pk_mul_f32 v[170:171], v[62:63], v[152:153]
	v_exp_f32_e32 v168, v168
	v_exp_f32_e32 v169, v169
	v_exp_f32_e32 v170, v170
	v_exp_f32_e32 v171, v171
	v_pk_add_f32 v[168:169], v[168:169], v[158:159]
	v_pk_add_f32 v[170:171], v[170:171], v[158:159]
	v_rcp_f32_e32 v168, v168
	v_rcp_f32_e32 v169, v169
	v_rcp_f32_e32 v170, v170
	v_rcp_f32_e32 v171, v171
	v_pk_mul_f32 v[52:53], v[52:53], v[60:61]
	v_pk_mul_f32 v[54:55], v[54:55], v[62:63]
	v_pk_mul_f32 v[52:53], v[52:53], v[168:169]
	v_pk_mul_f32 v[54:55], v[54:55], v[170:171]
	v_pk_mul_f32 v[56:57], v[56:57], v[150:151] op_sel_hi:[1,0]
	v_pk_mul_f32 v[58:59], v[58:59], v[150:151] op_sel_hi:[1,0]
	v_pk_mul_f32 v[48:49], v[48:49], v[150:151] op_sel_hi:[1,0]
	v_pk_mul_f32 v[50:51], v[50:51], v[150:151] op_sel_hi:[1,0]
	v_pk_mul_f32 v[168:169], v[56:57], v[152:153]
	v_pk_mul_f32 v[170:171], v[58:59], v[152:153]
	v_exp_f32_e32 v168, v168
	v_exp_f32_e32 v169, v169
	v_exp_f32_e32 v170, v170
	v_exp_f32_e32 v171, v171
	v_pk_add_f32 v[168:169], v[168:169], v[158:159]
	v_pk_add_f32 v[170:171], v[170:171], v[158:159]
	v_rcp_f32_e32 v168, v168
	v_rcp_f32_e32 v169, v169
	v_rcp_f32_e32 v170, v170
	v_rcp_f32_e32 v171, v171
	v_pk_mul_f32 v[48:49], v[48:49], v[56:57]
	v_pk_mul_f32 v[50:51], v[50:51], v[58:59]
	v_pk_mul_f32 v[48:49], v[48:49], v[168:169]
	v_pk_mul_f32 v[50:51], v[50:51], v[170:171]
	v_cvt_pk_bf16_f32 v164, v52, v53
	v_cvt_pk_bf16_f32 v165, v54, v55
	v_cvt_pk_bf16_f32 v166, v48, v49
	v_cvt_pk_bf16_f32 v167, v50, v51
	global_store_dwordx4 v149, v[164:167], s[14:15]
	s_nop 1
	v_add_u32_e32 v149, 0x16000, v149
	v_fmamk_f32 v150, v161, 0x3a800000, v151
	v_rsq_f32_e32 v150, v150
	s_nop 0
	v_pk_mul_f32 v[44:45], v[44:45], v[150:151] op_sel_hi:[1,0]
	v_pk_mul_f32 v[46:47], v[46:47], v[150:151] op_sel_hi:[1,0]
	v_pk_mul_f32 v[36:37], v[36:37], v[150:151] op_sel_hi:[1,0]
	v_pk_mul_f32 v[38:39], v[38:39], v[150:151] op_sel_hi:[1,0]
	v_pk_mul_f32 v[168:169], v[44:45], v[152:153]
	v_pk_mul_f32 v[170:171], v[46:47], v[152:153]
	v_exp_f32_e32 v168, v168
	v_exp_f32_e32 v169, v169
	v_exp_f32_e32 v170, v170
	v_exp_f32_e32 v171, v171
	v_pk_add_f32 v[168:169], v[168:169], v[158:159]
	v_pk_add_f32 v[170:171], v[170:171], v[158:159]
	v_rcp_f32_e32 v168, v168
	v_rcp_f32_e32 v169, v169
	v_rcp_f32_e32 v170, v170
	v_rcp_f32_e32 v171, v171
	v_pk_mul_f32 v[36:37], v[36:37], v[44:45]
	v_pk_mul_f32 v[38:39], v[38:39], v[46:47]
	v_pk_mul_f32 v[36:37], v[36:37], v[168:169]
	v_pk_mul_f32 v[38:39], v[38:39], v[170:171]
	v_pk_mul_f32 v[40:41], v[40:41], v[150:151] op_sel_hi:[1,0]
	v_pk_mul_f32 v[42:43], v[42:43], v[150:151] op_sel_hi:[1,0]
	v_pk_mul_f32 v[32:33], v[32:33], v[150:151] op_sel_hi:[1,0]
	v_pk_mul_f32 v[34:35], v[34:35], v[150:151] op_sel_hi:[1,0]
	v_pk_mul_f32 v[168:169], v[40:41], v[152:153]
	v_pk_mul_f32 v[170:171], v[42:43], v[152:153]
	v_exp_f32_e32 v168, v168
	v_exp_f32_e32 v169, v169
	v_exp_f32_e32 v170, v170
	v_exp_f32_e32 v171, v171
	v_pk_add_f32 v[168:169], v[168:169], v[158:159]
	v_pk_add_f32 v[170:171], v[170:171], v[158:159]
	v_rcp_f32_e32 v168, v168
	v_rcp_f32_e32 v169, v169
	v_rcp_f32_e32 v170, v170
	v_rcp_f32_e32 v171, v171
	v_pk_mul_f32 v[32:33], v[32:33], v[40:41]
	v_pk_mul_f32 v[34:35], v[34:35], v[42:43]
	v_pk_mul_f32 v[32:33], v[32:33], v[168:169]
	v_pk_mul_f32 v[34:35], v[34:35], v[170:171]
	v_cvt_pk_bf16_f32 v164, v36, v37
	v_cvt_pk_bf16_f32 v165, v38, v39
	v_cvt_pk_bf16_f32 v166, v32, v33
	v_cvt_pk_bf16_f32 v167, v34, v35
	global_store_dwordx4 v149, v[164:167], s[14:15]
	s_nop 1
	v_add_u32_e32 v149, 0x16000, v149
	v_fmamk_f32 v150, v162, 0x3a800000, v151
	v_rsq_f32_e32 v150, v150
	s_nop 0
	v_pk_mul_f32 v[28:29], v[28:29], v[150:151] op_sel_hi:[1,0]
	v_pk_mul_f32 v[30:31], v[30:31], v[150:151] op_sel_hi:[1,0]
	v_pk_mul_f32 v[20:21], v[20:21], v[150:151] op_sel_hi:[1,0]
	v_pk_mul_f32 v[22:23], v[22:23], v[150:151] op_sel_hi:[1,0]
	v_pk_mul_f32 v[168:169], v[28:29], v[152:153]
	v_pk_mul_f32 v[170:171], v[30:31], v[152:153]
	v_exp_f32_e32 v168, v168
	v_exp_f32_e32 v169, v169
	v_exp_f32_e32 v170, v170
	v_exp_f32_e32 v171, v171
	v_pk_add_f32 v[168:169], v[168:169], v[158:159]
	v_pk_add_f32 v[170:171], v[170:171], v[158:159]
	v_rcp_f32_e32 v168, v168
	v_rcp_f32_e32 v169, v169
	v_rcp_f32_e32 v170, v170
	v_rcp_f32_e32 v171, v171
	v_pk_mul_f32 v[20:21], v[20:21], v[28:29]
	v_pk_mul_f32 v[22:23], v[22:23], v[30:31]
	v_pk_mul_f32 v[20:21], v[20:21], v[168:169]
	v_pk_mul_f32 v[22:23], v[22:23], v[170:171]
	v_pk_mul_f32 v[24:25], v[24:25], v[150:151] op_sel_hi:[1,0]
	v_pk_mul_f32 v[26:27], v[26:27], v[150:151] op_sel_hi:[1,0]
	v_pk_mul_f32 v[16:17], v[16:17], v[150:151] op_sel_hi:[1,0]
	v_pk_mul_f32 v[18:19], v[18:19], v[150:151] op_sel_hi:[1,0]
	v_pk_mul_f32 v[168:169], v[24:25], v[152:153]
	v_pk_mul_f32 v[170:171], v[26:27], v[152:153]
	v_exp_f32_e32 v168, v168
	v_exp_f32_e32 v169, v169
	v_exp_f32_e32 v170, v170
	v_exp_f32_e32 v171, v171
	v_pk_add_f32 v[168:169], v[168:169], v[158:159]
	v_pk_add_f32 v[170:171], v[170:171], v[158:159]
	v_rcp_f32_e32 v168, v168
	v_rcp_f32_e32 v169, v169
	v_rcp_f32_e32 v170, v170
	v_rcp_f32_e32 v171, v171
	v_pk_mul_f32 v[16:17], v[16:17], v[24:25]
	v_pk_mul_f32 v[18:19], v[18:19], v[26:27]
	v_pk_mul_f32 v[16:17], v[16:17], v[168:169]
	v_pk_mul_f32 v[18:19], v[18:19], v[170:171]
	v_cvt_pk_bf16_f32 v164, v20, v21
	v_cvt_pk_bf16_f32 v165, v22, v23
	v_cvt_pk_bf16_f32 v166, v16, v17
	v_cvt_pk_bf16_f32 v167, v18, v19
	global_store_dwordx4 v149, v[164:167], s[14:15]
	s_nop 1
	v_add_u32_e32 v149, 0x16000, v149
	v_fmamk_f32 v150, v163, 0x3a800000, v151
	v_rsq_f32_e32 v150, v150
	s_nop 0
	v_pk_mul_f32 v[12:13], v[12:13], v[150:151] op_sel_hi:[1,0]
	v_pk_mul_f32 v[14:15], v[14:15], v[150:151] op_sel_hi:[1,0]
	v_pk_mul_f32 v[4:5], v[4:5], v[150:151] op_sel_hi:[1,0]
	v_pk_mul_f32 v[6:7], v[6:7], v[150:151] op_sel_hi:[1,0]
	v_pk_mul_f32 v[168:169], v[12:13], v[152:153]
	v_pk_mul_f32 v[170:171], v[14:15], v[152:153]
	v_exp_f32_e32 v168, v168
	v_exp_f32_e32 v169, v169
	v_exp_f32_e32 v170, v170
	v_exp_f32_e32 v171, v171
	v_pk_add_f32 v[168:169], v[168:169], v[158:159]
	v_pk_add_f32 v[170:171], v[170:171], v[158:159]
	v_rcp_f32_e32 v168, v168
	v_rcp_f32_e32 v169, v169
	v_rcp_f32_e32 v170, v170
	v_rcp_f32_e32 v171, v171
	v_pk_mul_f32 v[4:5], v[4:5], v[12:13]
	v_pk_mul_f32 v[6:7], v[6:7], v[14:15]
	v_pk_mul_f32 v[4:5], v[4:5], v[168:169]
	v_pk_mul_f32 v[6:7], v[6:7], v[170:171]
	v_pk_mul_f32 v[8:9], v[8:9], v[150:151] op_sel_hi:[1,0]
	v_pk_mul_f32 v[10:11], v[10:11], v[150:151] op_sel_hi:[1,0]
	v_pk_mul_f32 v[0:1], v[0:1], v[150:151] op_sel_hi:[1,0]
	v_pk_mul_f32 v[2:3], v[2:3], v[150:151] op_sel_hi:[1,0]
	v_pk_mul_f32 v[168:169], v[8:9], v[152:153]
	v_pk_mul_f32 v[170:171], v[10:11], v[152:153]
	v_exp_f32_e32 v168, v168
	v_exp_f32_e32 v169, v169
	v_exp_f32_e32 v170, v170
	v_exp_f32_e32 v171, v171
	v_pk_add_f32 v[168:169], v[168:169], v[158:159]
	v_pk_add_f32 v[170:171], v[170:171], v[158:159]
	v_rcp_f32_e32 v168, v168
	v_rcp_f32_e32 v169, v169
	v_rcp_f32_e32 v170, v170
	v_rcp_f32_e32 v171, v171
	v_pk_mul_f32 v[0:1], v[0:1], v[8:9]
	v_pk_mul_f32 v[2:3], v[2:3], v[10:11]
	v_pk_mul_f32 v[0:1], v[0:1], v[168:169]
	v_pk_mul_f32 v[2:3], v[2:3], v[170:171]
	v_cvt_pk_bf16_f32 v164, v4, v5
	v_cvt_pk_bf16_f32 v165, v6, v7
	v_cvt_pk_bf16_f32 v166, v0, v1
	v_cvt_pk_bf16_f32 v167, v2, v3
	global_store_dwordx4 v149, v[164:167], s[14:15]
.Lff_hend_7:
	s_mov_b64 s[6:7], -1
	s_branch .LBB0_1474

.LBB0_1867:
	v_readlane_b32 s0, v253, 0
	v_readlane_b32 s1, v253, 1
	s_cmp_lt_i32 s0, 13
	s_cselect_b64 s[0:1], -1, 0
	s_and_b64 s[6:7], s[0:1], s[6:7]
	s_andn2_b64 vcc, exec, s[6:7]
	s_cbranch_vccnz .LBB0_1888
	s_mov_b64 s[6:7], s[92:93]
	v_mov_b32_e32 v8, v180
	s_cmpk_gt_i32 s94, 0x1615
	s_nop 0
	v_readfirstlane_b32 s19, v8
	s_cbranch_scc1 .LBB0_1888
	v_lshlrev_b32_e32 v0, 4, v8
	s_waitcnt lgkmcnt(0)
	v_add_u32_e32 v1, 0x2000, v0
	v_ashrrev_i32_e32 v2, 31, v1
	v_lshrrev_b32_e32 v2, 22, v2
	v_add_u32_e32 v2, v1, v2
	v_ashrrev_i32_e32 v9, 10, v2
	v_mul_i32_i24_e32 v2, 0x400, v9
	v_sub_u32_e32 v1, v1, v2
	v_lshrrev_b32_e32 v2, 4, v1
	v_bitop3_b32 v1, v2, v1, 32 bitop3:0x6c
	v_ashrrev_i32_e32 v2, 31, v1
	v_lshrrev_b32_e32 v2, 26, v2
	v_add_u32_e32 v2, v1, v2
	v_lshlrev_b32_e32 v3, 3, v9
	v_ashrrev_i32_e32 v10, 6, v2
	v_and_b32_e32 v3, -16, v3
	v_add_u32_e32 v3, v10, v3
	v_and_b32_e32 v4, 3, v10
	s_mov_b32 s8, 0x1fffe0
	v_lshrrev_b32_e32 v5, 2, v3
	v_lshlrev_b32_e32 v6, 1, v3
	v_and_b32_e32 v2, 0xc0, v2
	v_and_or_b32 v4, v3, s8, v4
	v_and_b32_e32 v5, 4, v5
	v_and_b32_e32 v6, 24, v6
	v_sub_u32_e32 v1, v1, v2
	v_mov_b32_e32 v2, 1
	v_or3_b32 v4, v4, v5, v6
	v_lshlrev_b32_e32 v5, 5, v9
	v_ashrrev_i16_sdwa v1, v2, sext(v1) dst_sel:DWORD dst_unused:UNUSED_PAD src0_sel:DWORD src1_sel:BYTE_0
	v_and_b32_e32 v5, 32, v5
	v_bfe_i32 v11, v1, 0, 16
	v_add_lshl_u32 v1, v5, v11, 1
	v_lshl_add_u32 v128, v4, 11, v1
	v_lshl_add_u32 v130, v3, 11, v1
	v_bfe_i32 v1, v8, 27, 1
	v_lshrrev_b32_e32 v1, 22, v1
	v_add_u32_e32 v1, v0, v1
	v_and_b32_e32 v1, 0xfffffc00, v1
	v_sub_u32_e32 v0, v0, v1
	v_lshrrev_b32_e32 v1, 4, v0
	s_load_dwordx2 s[6:7], s[6:7], 0x120
	v_bitop3_b32 v1, v1, v0, 32 bitop3:0x6c
	v_ashrrev_i32_e32 v0, 31, v0
	v_lshrrev_b32_e32 v0, 26, v0
	v_add_u32_e32 v0, v1, v0
	v_ashrrev_i32_e32 v12, 6, v0
	v_ashrrev_i32_e32 v0, 31, v8
	v_lshrrev_b32_e32 v0, 26, v0
	s_waitcnt lgkmcnt(0)
	s_add_u32 s36, s6, 0x2e10b200
	v_add_u32_e32 v0, v8, v0
	s_addc_u32 s37, s7, 0
	v_ashrrev_i32_e32 v13, 6, v0
	s_add_u32 s38, s6, 0x1d80000
	v_lshlrev_b32_e32 v0, 3, v13
	s_addc_u32 s39, s7, 0
	s_ashr_i32 s20, s19, 6
	v_and_b32_e32 v0, -16, v0
	s_ashr_i32 s21, s19, 8
	s_lshl_b32 s40, s20, 10
	v_add_u32_e32 v0, v12, v0
	v_and_b32_e32 v3, 3, v12
	v_and_or_b32 v3, v0, s8, v3
	s_and_b64 s[8:9], s[16:17], exec
	s_cselect_b32 s8, s62, s61
	v_readlane_b32 s9, v253, 34
	v_lshrrev_b32_e32 v4, 2, v0
	v_lshlrev_b32_e32 v5, 1, v0
	s_add_i32 s8, s8, s9
	v_and_b32_e32 v4, 4, v4
	v_and_b32_e32 v5, 24, v5
	s_mul_hi_i32 s9, s8, 0x2e8ba2e9
	v_or3_b32 v3, v3, v4, v5
	v_mul_i32_i24_e32 v5, 64, v12
	s_lshr_b32 s10, s9, 31
	s_ashr_i32 s9, s9, 5
	v_sub_u32_e32 v1, v1, v5
	s_add_i32 s9, s9, s10
	v_lshlrev_b32_e32 v4, 5, v13
	v_ashrrev_i16_sdwa v1, v2, sext(v1) dst_sel:DWORD dst_unused:UNUSED_PAD src0_sel:DWORD src1_sel:BYTE_0
	s_lshl_b32 s10, s9, 3
	v_and_b32_e32 v4, 32, v4
	v_bfe_i32 v14, v1, 0, 16
	s_sub_i32 s11, 0x101, s10
	v_add_lshl_u32 v1, v4, v14, 1
	s_min_u32 s11, s11, 8
	s_mulk_i32 s9, 0xb0
	v_lshl_add_u32 v132, v3, 11, v1
	s_sub_i32 s12, s8, s9
	v_cvt_f32_ubyte0_e32 v3, s11
	v_cvt_f32_i32_e32 v2, s12
	v_rcp_iflag_f32_e32 v4, v3
	v_lshl_add_u32 v134, v0, 11, v1
	s_ashr_i32 s8, s12, 30
	s_or_b32 s13, s8, 1
	v_mul_f32_e32 v0, v2, v4
	v_trunc_f32_e32 v0, v0
	v_fma_f32 v1, -v0, v3, v2
	v_cvt_i32_f32_e32 v0, v0
	v_cmp_ge_f32_e64 s[8:9], |v1|, v3
	s_and_b64 s[8:9], s[8:9], exec
	s_cselect_b32 s8, s13, 0
	v_readfirstlane_b32 s9, v0
	s_add_i32 s18, s9, s8
	s_mul_i32 s8, s18, s11
	s_sub_i32 s8, s12, s8
	s_sext_i32_i16 s8, s8
	s_add_i32 s8, s10, s8
	s_ashr_i32 s9, s8, 31
	s_bfe_i64 s[12:13], s[18:19], 0x100000
	s_lshl_b64 s[10:11], s[8:9], 19
	s_lshl_b64 s[12:13], s[12:13], 19
	s_add_u32 s30, s38, s12
	s_addc_u32 s31, s39, s13
	s_add_i32 s41, s40, 0
	s_add_i32 m0, s41, 0x10000
	v_mov_b32_e32 v133, 0
	global_load_lds_dwordx4 v132, s[30:31]
	s_add_i32 m0, s41, 0x12000
	s_add_u32 s12, s30, 0x40000
	global_load_lds_dwordx4 v128, s[30:31]
	s_addc_u32 s13, s31, 0
	s_add_i32 m0, s41, 0x14000
	v_mov_b32_e32 v129, v133
	global_load_lds_dwordx4 v132, s[12:13]
	s_add_i32 m0, s41, 0x16000
	s_add_u32 s28, s36, s10
	s_addc_u32 s29, s37, s11
	s_add_i32 s42, s41, 0x2000
	global_load_lds_dwordx4 v128, s[12:13]
	s_mov_b32 m0, s41
	s_add_u32 s10, s28, 0x40000
	global_load_lds_dwordx4 v134, s[28:29]
	s_mov_b32 m0, s42
	s_addc_u32 s11, s29, 0
	s_add_i32 s43, s41, 0x4000
	global_load_lds_dwordx4 v130, s[28:29]
	s_mov_b32 m0, s43
	s_add_i32 s44, s41, 0x6000
	global_load_lds_dwordx4 v134, s[10:11]
	s_mov_b32 m0, s44
	v_mov_b32_e32 v135, v133
	global_load_lds_dwordx4 v130, s[10:11]
	v_mov_b32_e32 v131, v133
	s_cmp_eq_u32 s21, 1
	s_mov_b32 s45, 0
	s_mov_b32 s101, 0xf
	s_mov_b32 s100, 0xf
	v_lshl_add_u64 v[6:7], s[30:31], 0, v[132:133]
	v_lshl_add_u64 v[4:5], s[30:31], 0, v[128:129]
	v_lshl_add_u64 v[0:1], s[28:29], 0, v[134:135]
	s_cselect_b64 s[10:11], -1, 0
	s_cmp_lg_u32 s21, 1
	v_lshl_add_u64 v[2:3], s[28:29], 0, v[130:131]
	s_cbranch_scc1 .LBB0_1871
	s_barrier

.LBB0_1873:
	s_mov_b32 s101, s100
	s_andn2_b64 vcc, exec, s[6:7]
	s_mov_b32 s9, s20
	s_mov_b32 s8, s22
	s_mov_b64 s[30:31], s[26:27]
	s_mov_b64 s[28:29], s[24:25]
	s_cbranch_vccz .LBB0_1887
.LBB0_1874:
	s_add_i32 s45, s45, 1
	s_mul_i32 s6, s45, s47
	s_mul_hi_u32 s7, s45, s46
	s_add_i32 s7, s7, s6
	s_mul_i32 s6, s45, s46
	s_add_u32 s24, s6, s94
	s_addc_u32 s25, s7, s95
	s_mov_b32 s100, 0xf
	s_cmp_eq_u32 s46, 0x100
	s_cbranch_scc0 .Lhs_done_12
	s_cmp_eq_u32 s45, 22
	s_cbranch_scc0 .Lhs_done_12
	s_mov_b32 s25, 0
	s_mov_b32 s24, 0x7fffffff
	s_cmp_lt_u32 s94, 44
	s_cbranch_scc0 .Lhs_done_12
	s_lshr_b32 s24, s94, 1
	s_add_i32 s24, s24, 0x1600
	s_mov_b32 s100, 0x43
	s_bitcmp1_b32 s94, 0
	s_cbranch_scc0 .Lhs_done_12
	s_mov_b32 s100, 0x6c
.Lhs_done_12:
	v_cmp_gt_i64_e32 vcc, s[24:25], v[142:143]
	v_cmp_lt_i64_e64 s[6:7], s[24:25], v[140:141]
	s_cbranch_vccnz .LBB0_1880
	s_ashr_i32 s20, s24, 31
	s_lshr_b32 s20, s20, 29
	s_add_i32 s22, s24, s20
	s_and_b32 s20, s22, -8
	s_sub_i32 s23, s24, s20
	s_cmp_gt_i32 s23, 5
	s_mov_b64 s[20:21], -1
	s_cbranch_scc0 .LBB0_1877
	s_mul_i32 s20, s23, 0x2c2
	s_add_i32 s24, s20, 6
	s_mov_b64 s[20:21], 0

.LBB0_1881:
	ds_read_b128 v[144:147], v155
	ds_read_b128 v[148:151], v155 offset:1024
	ds_read_b128 v[160:163], v155 offset:2048
	ds_read_b128 v[164:167], v155 offset:3072
	ds_read_b128 v[168:171], v156
	ds_read_b128 v[172:175], v156 offset:1024
	ds_read_b128 v[176:179], v156 offset:2048
	ds_read_b128 v[182:185], v156 offset:3072
	s_add_u32 s30, s28, 0xfffc0080
	s_addc_u32 s31, s29, -1
	s_cmp_eq_u32 s61, 12
	s_cselect_b32 s35, s23, s31
	s_cselect_b32 s34, s56, s30
	s_cselect_b32 s31, s21, s59
	s_cselect_b32 s30, s57, s58
	v_lshl_add_u64 v[152:153], s[28:29], 0, v[136:137]
	s_add_i32 m0, s41, 0xc000
	ds_read_b128 v[186:189], v157
	ds_read_b128 v[190:193], v157 offset:1024
	ds_read_b128 v[194:197], v157 offset:2048
	ds_read_b128 v[198:201], v157 offset:3072
	ds_read_b128 v[202:205], v157 offset:4096
	ds_read_b128 v[206:209], v157 offset:5120
	ds_read_b128 v[210:213], v157 offset:6144
	ds_read_b128 v[214:217], v157 offset:7168
	global_load_lds_dwordx4 v[152:153], off
	v_lshl_add_u64 v[152:153], s[28:29], 0, v[138:139]
	s_add_i32 m0, s41, 0xe000
	s_nop 0
	global_load_lds_dwordx4 v[152:153], off
	s_waitcnt vmcnt(8)
	s_waitcnt lgkmcnt(0)
	s_barrier
	s_setprio 1
	s_waitcnt lgkmcnt(0)
	s_bitcmp1_b32 s101, 0
	s_cbranch_scc0 .Lmf_12_0
	v_mfma_f32_16x16x32_bf16 v[124:127], v[144:147], v[186:189], v[124:127]
	v_mfma_f32_16x16x32_bf16 v[120:123], v[160:163], v[186:189], v[120:123]
	v_mfma_f32_16x16x32_bf16 v[108:111], v[144:147], v[194:197], v[108:111]
	v_mfma_f32_16x16x32_bf16 v[104:107], v[160:163], v[194:197], v[104:107]
	v_mfma_f32_16x16x32_bf16 v[92:95], v[144:147], v[202:205], v[92:95]
	v_mfma_f32_16x16x32_bf16 v[88:91], v[160:163], v[202:205], v[88:91]
	v_mfma_f32_16x16x32_bf16 v[76:79], v[144:147], v[210:213], v[76:79]
	v_mfma_f32_16x16x32_bf16 v[72:75], v[160:163], v[210:213], v[72:75]
	v_mfma_f32_16x16x32_bf16 v[124:127], v[148:151], v[190:193], v[124:127]
	v_mfma_f32_16x16x32_bf16 v[120:123], v[164:167], v[190:193], v[120:123]
	v_mfma_f32_16x16x32_bf16 v[108:111], v[148:151], v[198:201], v[108:111]
	v_mfma_f32_16x16x32_bf16 v[104:107], v[164:167], v[198:201], v[104:107]
	v_mfma_f32_16x16x32_bf16 v[92:95], v[148:151], v[206:209], v[92:95]
	v_mfma_f32_16x16x32_bf16 v[88:91], v[164:167], v[206:209], v[88:91]
	v_mfma_f32_16x16x32_bf16 v[76:79], v[148:151], v[214:217], v[76:79]
	v_mfma_f32_16x16x32_bf16 v[72:75], v[164:167], v[214:217], v[72:75]

.Lmf_12_1:
	s_setprio 0
	s_barrier
	s_add_i32 s62, s52, s40
	v_lshl_add_u64 v[152:153], s[30:31], 0, v[132:133]
	s_mov_b32 m0, s62
	ds_read_b128 v[186:189], v157 offset:16384
	ds_read_b128 v[190:193], v157 offset:17408
	ds_read_b128 v[194:197], v157 offset:18432
	ds_read_b128 v[198:201], v157 offset:19456
	ds_read_b128 v[202:205], v157 offset:20480
	ds_read_b128 v[206:209], v157 offset:21504
	ds_read_b128 v[210:213], v157 offset:22528
	ds_read_b128 v[214:217], v157 offset:23552
	global_load_lds_dwordx4 v[152:153], off
	s_add_i32 m0, s62, 0x2000
	s_add_u32 s62, s30, 0x40000
	v_lshl_add_u64 v[218:219], s[30:31], 0, v[128:129]
	s_addc_u32 s63, s31, 0
	s_add_i32 s64, s53, s40
	global_load_lds_dwordx4 v[218:219], off
	v_lshl_add_u64 v[220:221], s[62:63], 0, v[132:133]
	s_mov_b32 m0, s64
	v_lshl_add_u64 v[222:223], s[34:35], 0, v[130:131]
	global_load_lds_dwordx4 v[220:221], off
	v_lshl_add_u64 v[220:221], s[62:63], 0, v[128:129]
	s_add_i32 m0, s64, 0x2000
	s_nop 0
	global_load_lds_dwordx4 v[220:221], off
	v_lshl_add_u64 v[220:221], s[34:35], 0, v[134:135]
	s_mov_b32 m0, s41
	s_nop 0
	global_load_lds_dwordx4 v[220:221], off
	s_mov_b32 m0, s42
	s_nop 0
	global_load_lds_dwordx4 v[222:223], off
	s_waitcnt vmcnt(8)
	s_waitcnt lgkmcnt(0)
	s_barrier
	s_setprio 1
	s_waitcnt lgkmcnt(0)
	s_bitcmp1_b32 s101, 2
	s_cbranch_scc0 .Lmf_12_2
	v_mfma_f32_16x16x32_bf16 v[60:63], v[144:147], v[186:189], v[60:63]
	v_mfma_f32_16x16x32_bf16 v[56:59], v[160:163], v[186:189], v[56:59]
	v_mfma_f32_16x16x32_bf16 v[44:47], v[144:147], v[194:197], v[44:47]
	v_mfma_f32_16x16x32_bf16 v[40:43], v[160:163], v[194:197], v[40:43]
	v_mfma_f32_16x16x32_bf16 v[28:31], v[144:147], v[202:205], v[28:31]
	v_mfma_f32_16x16x32_bf16 v[24:27], v[160:163], v[202:205], v[24:27]
	v_mfma_f32_16x16x32_bf16 v[12:15], v[144:147], v[210:213], v[12:15]
	v_mfma_f32_16x16x32_bf16 v[8:11], v[160:163], v[210:213], v[8:11]
	v_mfma_f32_16x16x32_bf16 v[60:63], v[148:151], v[190:193], v[60:63]
	v_mfma_f32_16x16x32_bf16 v[56:59], v[164:167], v[190:193], v[56:59]
	v_mfma_f32_16x16x32_bf16 v[44:47], v[148:151], v[198:201], v[44:47]
	v_mfma_f32_16x16x32_bf16 v[40:43], v[164:167], v[198:201], v[40:43]
	v_mfma_f32_16x16x32_bf16 v[28:31], v[148:151], v[206:209], v[28:31]
	v_mfma_f32_16x16x32_bf16 v[24:27], v[164:167], v[206:209], v[24:27]
	v_mfma_f32_16x16x32_bf16 v[12:15], v[148:151], v[214:217], v[12:15]
	v_mfma_f32_16x16x32_bf16 v[8:11], v[164:167], v[214:217], v[8:11]

.Lmf_12_3:
	s_setprio 0
	s_barrier
	s_add_i32 s62, 0, 0x18000
	v_add_u32_e32 v159, s62, v154
	s_add_i32 s63, 0, 0x1c000
	ds_read_b128 v[144:147], v159
	ds_read_b128 v[148:151], v159 offset:1024
	ds_read_b128 v[160:163], v159 offset:2048
	ds_read_b128 v[164:167], v159 offset:3072
	v_add_u32_e32 v159, s63, v154
	ds_read_b128 v[168:171], v159
	ds_read_b128 v[172:175], v159 offset:1024
	ds_read_b128 v[176:179], v159 offset:2048
	ds_read_b128 v[182:185], v159 offset:3072
	s_add_u32 s34, s34, 0x40000
	s_addc_u32 s35, s35, 0
	s_mov_b32 m0, s43
	v_lshl_add_u64 v[224:225], s[34:35], 0, v[134:135]
	ds_read_b128 v[186:189], v157 offset:32768
	ds_read_b128 v[190:193], v157 offset:33792
	ds_read_b128 v[194:197], v157 offset:34816
	ds_read_b128 v[198:201], v157 offset:35840
	ds_read_b128 v[202:205], v157 offset:36864
	ds_read_b128 v[206:209], v157 offset:37888
	ds_read_b128 v[210:213], v157 offset:38912
	ds_read_b128 v[214:217], v157 offset:39936
	global_load_lds_dwordx4 v[224:225], off
	v_lshl_add_u64 v[224:225], s[34:35], 0, v[130:131]
	s_mov_b32 m0, s44
	s_nop 0
	global_load_lds_dwordx4 v[224:225], off
	s_waitcnt vmcnt(8)
	s_waitcnt lgkmcnt(0)
	s_barrier
	s_setprio 1
	s_waitcnt lgkmcnt(0)
	s_bitcmp1_b32 s101, 0
	s_cbranch_scc0 .Lmf_12_4
	v_mfma_f32_16x16x32_bf16 v[124:127], v[144:147], v[186:189], v[124:127]
	v_mfma_f32_16x16x32_bf16 v[120:123], v[160:163], v[186:189], v[120:123]
	v_mfma_f32_16x16x32_bf16 v[108:111], v[144:147], v[194:197], v[108:111]
	v_mfma_f32_16x16x32_bf16 v[104:107], v[160:163], v[194:197], v[104:107]
	v_mfma_f32_16x16x32_bf16 v[92:95], v[144:147], v[202:205], v[92:95]
	v_mfma_f32_16x16x32_bf16 v[88:91], v[160:163], v[202:205], v[88:91]
	v_mfma_f32_16x16x32_bf16 v[76:79], v[144:147], v[210:213], v[76:79]
	v_mfma_f32_16x16x32_bf16 v[72:75], v[160:163], v[210:213], v[72:75]
	v_mfma_f32_16x16x32_bf16 v[124:127], v[148:151], v[190:193], v[124:127]
	v_mfma_f32_16x16x32_bf16 v[120:123], v[164:167], v[190:193], v[120:123]
	v_mfma_f32_16x16x32_bf16 v[108:111], v[148:151], v[198:201], v[108:111]
	v_mfma_f32_16x16x32_bf16 v[104:107], v[164:167], v[198:201], v[104:107]
	v_mfma_f32_16x16x32_bf16 v[92:95], v[148:151], v[206:209], v[92:95]
	v_mfma_f32_16x16x32_bf16 v[88:91], v[164:167], v[206:209], v[88:91]
	v_mfma_f32_16x16x32_bf16 v[76:79], v[148:151], v[214:217], v[76:79]
	v_mfma_f32_16x16x32_bf16 v[72:75], v[164:167], v[214:217], v[72:75]

.Lmf_12_5:
	s_setprio 0
	s_barrier
	s_add_i32 s34, s62, s40
	v_lshl_add_u64 v[152:153], v[152:153], 0, s[16:17]
	s_mov_b32 m0, s34
	ds_read_b128 v[186:189], v157 offset:49152
	ds_read_b128 v[190:193], v157 offset:50176
	ds_read_b128 v[194:197], v157 offset:51200
	ds_read_b128 v[198:201], v157 offset:52224
	ds_read_b128 v[202:205], v157 offset:53248
	ds_read_b128 v[206:209], v157 offset:54272
	ds_read_b128 v[210:213], v157 offset:55296
	ds_read_b128 v[214:217], v157 offset:56320
	global_load_lds_dwordx4 v[152:153], off
	s_add_i32 m0, s34, 0x2000
	s_add_u32 s30, s30, 0x40080
	v_lshl_add_u64 v[152:153], v[218:219], 0, s[16:17]
	s_addc_u32 s31, s31, 0
	s_add_i32 s34, s63, s40
	global_load_lds_dwordx4 v[152:153], off
	v_lshl_add_u64 v[152:153], s[30:31], 0, v[132:133]
	s_mov_b32 m0, s34
	s_nop 0
	global_load_lds_dwordx4 v[152:153], off
	v_lshl_add_u64 v[152:153], s[30:31], 0, v[128:129]
	s_add_i32 m0, s34, 0x2000
	s_nop 0
	global_load_lds_dwordx4 v[152:153], off
	v_lshl_add_u64 v[152:153], v[220:221], 0, s[16:17]
	s_mov_b32 m0, s50
	s_nop 0
	global_load_lds_dwordx4 v[152:153], off
	v_lshl_add_u64 v[152:153], v[222:223], 0, s[16:17]
	s_mov_b32 m0, s51
	s_nop 0
	global_load_lds_dwordx4 v[152:153], off
	s_waitcnt vmcnt(8)
	s_waitcnt lgkmcnt(0)
	s_barrier
	s_setprio 1
	s_waitcnt lgkmcnt(0)
	s_bitcmp1_b32 s101, 2
	s_cbranch_scc0 .Lmf_12_6
	v_mfma_f32_16x16x32_bf16 v[60:63], v[144:147], v[186:189], v[60:63]
	v_mfma_f32_16x16x32_bf16 v[56:59], v[160:163], v[186:189], v[56:59]
	v_mfma_f32_16x16x32_bf16 v[44:47], v[144:147], v[194:197], v[44:47]
	v_mfma_f32_16x16x32_bf16 v[40:43], v[160:163], v[194:197], v[40:43]
	v_mfma_f32_16x16x32_bf16 v[28:31], v[144:147], v[202:205], v[28:31]
	v_mfma_f32_16x16x32_bf16 v[24:27], v[160:163], v[202:205], v[24:27]
	v_mfma_f32_16x16x32_bf16 v[12:15], v[144:147], v[210:213], v[12:15]
	v_mfma_f32_16x16x32_bf16 v[8:11], v[160:163], v[210:213], v[8:11]
	v_mfma_f32_16x16x32_bf16 v[60:63], v[148:151], v[190:193], v[60:63]
	v_mfma_f32_16x16x32_bf16 v[56:59], v[164:167], v[190:193], v[56:59]
	v_mfma_f32_16x16x32_bf16 v[44:47], v[148:151], v[198:201], v[44:47]
	v_mfma_f32_16x16x32_bf16 v[40:43], v[164:167], v[198:201], v[40:43]
	v_mfma_f32_16x16x32_bf16 v[28:31], v[148:151], v[206:209], v[28:31]
	v_mfma_f32_16x16x32_bf16 v[24:27], v[164:167], v[206:209], v[24:27]
	v_mfma_f32_16x16x32_bf16 v[12:15], v[148:151], v[214:217], v[12:15]
	v_mfma_f32_16x16x32_bf16 v[8:11], v[164:167], v[214:217], v[8:11]

.Lmf_12_7:
	s_setprio 0
	s_barrier
	s_add_i32 s61, s61, 2
	s_add_u32 s28, s28, 0x100
	s_addc_u32 s29, s29, 0
	s_add_u32 s58, s58, 0x100
	s_addc_u32 s59, s59, 0
	s_cmp_gt_u32 s61, 13
	s_cbranch_scc0 .LBB0_1881
	s_and_b64 vcc, exec, s[18:19]
	s_cbranch_vccz .LBB0_1884
	s_barrier
.LBB0_1884:
	s_bitcmp1_b32 s101, 6
	s_cbranch_scc0 .Lff_full_12
	s_bitcmp1_b32 s101, 5
	s_cbranch_scc1 .Lff_h1_12
	v_and_b32_e32 v144, 15, v180
	v_bfe_u32 v145, v180, 4, 2
	s_lshl_b32 s98, s8, 8
	s_add_i32 s98, s98, s48
	v_add_u32_e32 v146, s98, v144
	v_lshlrev_b32_e32 v147, 2, v146
	s_lshl_b32 s98, s9, 7
	s_add_i32 s98, s98, s49
	v_lshl_add_u32 v148, v145, 3, s98
	v_mul_u32_u24_e32 v149, 0x1600, v146
	v_lshl_add_u32 v149, v148, 1, v149
	global_load_dword v160, v147, s[12:13] offset:0
	global_load_dword v161, v147, s[12:13] offset:64
	global_load_dword v162, v147, s[12:13] offset:128
	global_load_dword v163, v147, s[12:13] offset:192
	v_mov_b32_e32 v151, 0x358637bd
	v_mov_b32_e32 v152, 0xbfb8aa3b
	v_mov_b32_e32 v153, 0xbfb8aa3b
	v_mov_b32_e32 v158, 1.0
	v_mov_b32_e32 v159, 1.0
	s_waitcnt vmcnt(0)
	v_fmamk_f32 v150, v160, 0x3a800000, v151
	v_rsq_f32_e32 v150, v150
	s_nop 0
	v_pk_mul_f32 v[124:125], v[124:125], v[150:151] op_sel_hi:[1,0]
	v_pk_mul_f32 v[126:127], v[126:127], v[150:151] op_sel_hi:[1,0]
	v_pk_mul_f32 v[116:117], v[116:117], v[150:151] op_sel_hi:[1,0]
	v_pk_mul_f32 v[118:119], v[118:119], v[150:151] op_sel_hi:[1,0]
	v_pk_mul_f32 v[168:169], v[124:125], v[152:153]
	v_pk_mul_f32 v[170:171], v[126:127], v[152:153]
	v_exp_f32_e32 v168, v168
	v_exp_f32_e32 v169, v169
	v_exp_f32_e32 v170, v170
	v_exp_f32_e32 v171, v171
	v_pk_add_f32 v[168:169], v[168:169], v[158:159]
	v_pk_add_f32 v[170:171], v[170:171], v[158:159]
	v_rcp_f32_e32 v168, v168
	v_rcp_f32_e32 v169, v169
	v_rcp_f32_e32 v170, v170
	v_rcp_f32_e32 v171, v171
	v_pk_mul_f32 v[116:117], v[116:117], v[124:125]
	v_pk_mul_f32 v[118:119], v[118:119], v[126:127]
	v_pk_mul_f32 v[116:117], v[116:117], v[168:169]
	v_pk_mul_f32 v[118:119], v[118:119], v[170:171]
	v_pk_mul_f32 v[120:121], v[120:121], v[150:151] op_sel_hi:[1,0]
	v_pk_mul_f32 v[122:123], v[122:123], v[150:151] op_sel_hi:[1,0]
	v_pk_mul_f32 v[112:113], v[112:113], v[150:151] op_sel_hi:[1,0]
	v_pk_mul_f32 v[114:115], v[114:115], v[150:151] op_sel_hi:[1,0]
	v_pk_mul_f32 v[168:169], v[120:121], v[152:153]
	v_pk_mul_f32 v[170:171], v[122:123], v[152:153]
	v_exp_f32_e32 v168, v168
	v_exp_f32_e32 v169, v169
	v_exp_f32_e32 v170, v170
	v_exp_f32_e32 v171, v171
	v_pk_add_f32 v[168:169], v[168:169], v[158:159]
	v_pk_add_f32 v[170:171], v[170:171], v[158:159]
	v_rcp_f32_e32 v168, v168
	v_rcp_f32_e32 v169, v169
	v_rcp_f32_e32 v170, v170
	v_rcp_f32_e32 v171, v171
	v_pk_mul_f32 v[112:113], v[112:113], v[120:121]
	v_pk_mul_f32 v[114:115], v[114:115], v[122:123]
	v_pk_mul_f32 v[112:113], v[112:113], v[168:169]
	v_pk_mul_f32 v[114:115], v[114:115], v[170:171]
	v_cvt_pk_bf16_f32 v164, v116, v117
	v_cvt_pk_bf16_f32 v165, v118, v119
	v_cvt_pk_bf16_f32 v166, v112, v113
	v_cvt_pk_bf16_f32 v167, v114, v115
	global_store_dwordx4 v149, v[164:167], s[14:15]
	s_nop 1
	v_add_u32_e32 v149, 0x16000, v149
	v_fmamk_f32 v150, v161, 0x3a800000, v151
	v_rsq_f32_e32 v150, v150
	s_nop 0
	v_pk_mul_f32 v[108:109], v[108:109], v[150:151] op_sel_hi:[1,0]
	v_pk_mul_f32 v[110:111], v[110:111], v[150:151] op_sel_hi:[1,0]
	v_pk_mul_f32 v[100:101], v[100:101], v[150:151] op_sel_hi:[1,0]
	v_pk_mul_f32 v[102:103], v[102:103], v[150:151] op_sel_hi:[1,0]
	v_pk_mul_f32 v[168:169], v[108:109], v[152:153]
	v_pk_mul_f32 v[170:171], v[110:111], v[152:153]
	v_exp_f32_e32 v168, v168
	v_exp_f32_e32 v169, v169
	v_exp_f32_e32 v170, v170
	v_exp_f32_e32 v171, v171
	v_pk_add_f32 v[168:169], v[168:169], v[158:159]
	v_pk_add_f32 v[170:171], v[170:171], v[158:159]
	v_rcp_f32_e32 v168, v168
	v_rcp_f32_e32 v169, v169
	v_rcp_f32_e32 v170, v170
	v_rcp_f32_e32 v171, v171
	v_pk_mul_f32 v[100:101], v[100:101], v[108:109]
	v_pk_mul_f32 v[102:103], v[102:103], v[110:111]
	v_pk_mul_f32 v[100:101], v[100:101], v[168:169]
	v_pk_mul_f32 v[102:103], v[102:103], v[170:171]
	v_pk_mul_f32 v[104:105], v[104:105], v[150:151] op_sel_hi:[1,0]
	v_pk_mul_f32 v[106:107], v[106:107], v[150:151] op_sel_hi:[1,0]
	v_pk_mul_f32 v[96:97], v[96:97], v[150:151] op_sel_hi:[1,0]
	v_pk_mul_f32 v[98:99], v[98:99], v[150:151] op_sel_hi:[1,0]
	v_pk_mul_f32 v[168:169], v[104:105], v[152:153]
	v_pk_mul_f32 v[170:171], v[106:107], v[152:153]
	v_exp_f32_e32 v168, v168
	v_exp_f32_e32 v169, v169
	v_exp_f32_e32 v170, v170
	v_exp_f32_e32 v171, v171
	v_pk_add_f32 v[168:169], v[168:169], v[158:159]
	v_pk_add_f32 v[170:171], v[170:171], v[158:159]
	v_rcp_f32_e32 v168, v168
	v_rcp_f32_e32 v169, v169
	v_rcp_f32_e32 v170, v170
	v_rcp_f32_e32 v171, v171
	v_pk_mul_f32 v[96:97], v[96:97], v[104:105]
	v_pk_mul_f32 v[98:99], v[98:99], v[106:107]
	v_pk_mul_f32 v[96:97], v[96:97], v[168:169]
	v_pk_mul_f32 v[98:99], v[98:99], v[170:171]
	v_cvt_pk_bf16_f32 v164, v100, v101
	v_cvt_pk_bf16_f32 v165, v102, v103
	v_cvt_pk_bf16_f32 v166, v96, v97
	v_cvt_pk_bf16_f32 v167, v98, v99
	global_store_dwordx4 v149, v[164:167], s[14:15]
	s_nop 1
	v_add_u32_e32 v149, 0x16000, v149
	v_fmamk_f32 v150, v162, 0x3a800000, v151
	v_rsq_f32_e32 v150, v150
	s_nop 0
	v_pk_mul_f32 v[92:93], v[92:93], v[150:151] op_sel_hi:[1,0]
	v_pk_mul_f32 v[94:95], v[94:95], v[150:151] op_sel_hi:[1,0]
	v_pk_mul_f32 v[84:85], v[84:85], v[150:151] op_sel_hi:[1,0]
	v_pk_mul_f32 v[86:87], v[86:87], v[150:151] op_sel_hi:[1,0]
	v_pk_mul_f32 v[168:169], v[92:93], v[152:153]
	v_pk_mul_f32 v[170:171], v[94:95], v[152:153]
	v_exp_f32_e32 v168, v168
	v_exp_f32_e32 v169, v169
	v_exp_f32_e32 v170, v170
	v_exp_f32_e32 v171, v171
	v_pk_add_f32 v[168:169], v[168:169], v[158:159]
	v_pk_add_f32 v[170:171], v[170:171], v[158:159]
	v_rcp_f32_e32 v168, v168
	v_rcp_f32_e32 v169, v169
	v_rcp_f32_e32 v170, v170
	v_rcp_f32_e32 v171, v171
	v_pk_mul_f32 v[84:85], v[84:85], v[92:93]
	v_pk_mul_f32 v[86:87], v[86:87], v[94:95]
	v_pk_mul_f32 v[84:85], v[84:85], v[168:169]
	v_pk_mul_f32 v[86:87], v[86:87], v[170:171]
	v_pk_mul_f32 v[88:89], v[88:89], v[150:151] op_sel_hi:[1,0]
	v_pk_mul_f32 v[90:91], v[90:91], v[150:151] op_sel_hi:[1,0]
	v_pk_mul_f32 v[80:81], v[80:81], v[150:151] op_sel_hi:[1,0]
	v_pk_mul_f32 v[82:83], v[82:83], v[150:151] op_sel_hi:[1,0]
	v_pk_mul_f32 v[168:169], v[88:89], v[152:153]
	v_pk_mul_f32 v[170:171], v[90:91], v[152:153]
	v_exp_f32_e32 v168, v168
	v_exp_f32_e32 v169, v169
	v_exp_f32_e32 v170, v170
	v_exp_f32_e32 v171, v171
	v_pk_add_f32 v[168:169], v[168:169], v[158:159]
	v_pk_add_f32 v[170:171], v[170:171], v[158:159]
	v_rcp_f32_e32 v168, v168
	v_rcp_f32_e32 v169, v169
	v_rcp_f32_e32 v170, v170
	v_rcp_f32_e32 v171, v171
	v_pk_mul_f32 v[80:81], v[80:81], v[88:89]
	v_pk_mul_f32 v[82:83], v[82:83], v[90:91]
	v_pk_mul_f32 v[80:81], v[80:81], v[168:169]
	v_pk_mul_f32 v[82:83], v[82:83], v[170:171]
	v_cvt_pk_bf16_f32 v164, v84, v85
	v_cvt_pk_bf16_f32 v165, v86, v87
	v_cvt_pk_bf16_f32 v166, v80, v81
	v_cvt_pk_bf16_f32 v167, v82, v83
	global_store_dwordx4 v149, v[164:167], s[14:15]
	s_nop 1
	v_add_u32_e32 v149, 0x16000, v149
	v_fmamk_f32 v150, v163, 0x3a800000, v151
	v_rsq_f32_e32 v150, v150
	s_nop 0
	v_pk_mul_f32 v[76:77], v[76:77], v[150:151] op_sel_hi:[1,0]
	v_pk_mul_f32 v[78:79], v[78:79], v[150:151] op_sel_hi:[1,0]
	v_pk_mul_f32 v[68:69], v[68:69], v[150:151] op_sel_hi:[1,0]
	v_pk_mul_f32 v[70:71], v[70:71], v[150:151] op_sel_hi:[1,0]
	v_pk_mul_f32 v[168:169], v[76:77], v[152:153]
	v_pk_mul_f32 v[170:171], v[78:79], v[152:153]
	v_exp_f32_e32 v168, v168
	v_exp_f32_e32 v169, v169
	v_exp_f32_e32 v170, v170
	v_exp_f32_e32 v171, v171
	v_pk_add_f32 v[168:169], v[168:169], v[158:159]
	v_pk_add_f32 v[170:171], v[170:171], v[158:159]
	v_rcp_f32_e32 v168, v168
	v_rcp_f32_e32 v169, v169
	v_rcp_f32_e32 v170, v170
	v_rcp_f32_e32 v171, v171
	v_pk_mul_f32 v[68:69], v[68:69], v[76:77]
	v_pk_mul_f32 v[70:71], v[70:71], v[78:79]
	v_pk_mul_f32 v[68:69], v[68:69], v[168:169]
	v_pk_mul_f32 v[70:71], v[70:71], v[170:171]
	v_pk_mul_f32 v[72:73], v[72:73], v[150:151] op_sel_hi:[1,0]
	v_pk_mul_f32 v[74:75], v[74:75], v[150:151] op_sel_hi:[1,0]
	v_pk_mul_f32 v[64:65], v[64:65], v[150:151] op_sel_hi:[1,0]
	v_pk_mul_f32 v[66:67], v[66:67], v[150:151] op_sel_hi:[1,0]
	v_pk_mul_f32 v[168:169], v[72:73], v[152:153]
	v_pk_mul_f32 v[170:171], v[74:75], v[152:153]
	v_exp_f32_e32 v168, v168
	v_exp_f32_e32 v169, v169
	v_exp_f32_e32 v170, v170
	v_exp_f32_e32 v171, v171
	v_pk_add_f32 v[168:169], v[168:169], v[158:159]
	v_pk_add_f32 v[170:171], v[170:171], v[158:159]
	v_rcp_f32_e32 v168, v168
	v_rcp_f32_e32 v169, v169
	v_rcp_f32_e32 v170, v170
	v_rcp_f32_e32 v171, v171
	v_pk_mul_f32 v[64:65], v[64:65], v[72:73]
	v_pk_mul_f32 v[66:67], v[66:67], v[74:75]
	v_pk_mul_f32 v[64:65], v[64:65], v[168:169]
	v_pk_mul_f32 v[66:67], v[66:67], v[170:171]
	v_cvt_pk_bf16_f32 v164, v68, v69
	v_cvt_pk_bf16_f32 v165, v70, v71
	v_cvt_pk_bf16_f32 v166, v64, v65
	v_cvt_pk_bf16_f32 v167, v66, v67
	global_store_dwordx4 v149, v[164:167], s[14:15]
	s_branch .Lff_hend_12
.Lff_h1_12:
	v_and_b32_e32 v144, 15, v180
	v_bfe_u32 v145, v180, 4, 2
	s_lshl_b32 s98, s8, 8
	s_add_i32 s98, s98, s48
	s_add_i32 s98, s98, 0x80
	v_add_u32_e32 v146, s98, v144
	v_lshlrev_b32_e32 v147, 2, v146
	s_lshl_b32 s98, s9, 7
	s_add_i32 s98, s98, s49
	v_lshl_add_u32 v148, v145, 3, s98
	v_mul_u32_u24_e32 v149, 0x1600, v146
	v_lshl_add_u32 v149, v148, 1, v149
	global_load_dword v160, v147, s[12:13] offset:0
	global_load_dword v161, v147, s[12:13] offset:64
	global_load_dword v162, v147, s[12:13] offset:128
	global_load_dword v163, v147, s[12:13] offset:192
	v_mov_b32_e32 v151, 0x358637bd
	v_mov_b32_e32 v152, 0xbfb8aa3b
	v_mov_b32_e32 v153, 0xbfb8aa3b
	v_mov_b32_e32 v158, 1.0
	v_mov_b32_e32 v159, 1.0
	s_waitcnt vmcnt(0)
	v_fmamk_f32 v150, v160, 0x3a800000, v151
	v_rsq_f32_e32 v150, v150
	s_nop 0
	v_pk_mul_f32 v[60:61], v[60:61], v[150:151] op_sel_hi:[1,0]
	v_pk_mul_f32 v[62:63], v[62:63], v[150:151] op_sel_hi:[1,0]
	v_pk_mul_f32 v[52:53], v[52:53], v[150:151] op_sel_hi:[1,0]
	v_pk_mul_f32 v[54:55], v[54:55], v[150:151] op_sel_hi:[1,0]
	v_pk_mul_f32 v[168:169], v[60:61], v[152:153]
	v_pk_mul_f32 v[170:171], v[62:63], v[152:153]
	v_exp_f32_e32 v168, v168
	v_exp_f32_e32 v169, v169
	v_exp_f32_e32 v170, v170
	v_exp_f32_e32 v171, v171
	v_pk_add_f32 v[168:169], v[168:169], v[158:159]
	v_pk_add_f32 v[170:171], v[170:171], v[158:159]
	v_rcp_f32_e32 v168, v168
	v_rcp_f32_e32 v169, v169
	v_rcp_f32_e32 v170, v170
	v_rcp_f32_e32 v171, v171
	v_pk_mul_f32 v[52:53], v[52:53], v[60:61]
	v_pk_mul_f32 v[54:55], v[54:55], v[62:63]
	v_pk_mul_f32 v[52:53], v[52:53], v[168:169]
	v_pk_mul_f32 v[54:55], v[54:55], v[170:171]
	v_pk_mul_f32 v[56:57], v[56:57], v[150:151] op_sel_hi:[1,0]
	v_pk_mul_f32 v[58:59], v[58:59], v[150:151] op_sel_hi:[1,0]
	v_pk_mul_f32 v[48:49], v[48:49], v[150:151] op_sel_hi:[1,0]
	v_pk_mul_f32 v[50:51], v[50:51], v[150:151] op_sel_hi:[1,0]
	v_pk_mul_f32 v[168:169], v[56:57], v[152:153]
	v_pk_mul_f32 v[170:171], v[58:59], v[152:153]
	v_exp_f32_e32 v168, v168
	v_exp_f32_e32 v169, v169
	v_exp_f32_e32 v170, v170
	v_exp_f32_e32 v171, v171
	v_pk_add_f32 v[168:169], v[168:169], v[158:159]
	v_pk_add_f32 v[170:171], v[170:171], v[158:159]
	v_rcp_f32_e32 v168, v168
	v_rcp_f32_e32 v169, v169
	v_rcp_f32_e32 v170, v170
	v_rcp_f32_e32 v171, v171
	v_pk_mul_f32 v[48:49], v[48:49], v[56:57]
	v_pk_mul_f32 v[50:51], v[50:51], v[58:59]
	v_pk_mul_f32 v[48:49], v[48:49], v[168:169]
	v_pk_mul_f32 v[50:51], v[50:51], v[170:171]
	v_cvt_pk_bf16_f32 v164, v52, v53
	v_cvt_pk_bf16_f32 v165, v54, v55
	v_cvt_pk_bf16_f32 v166, v48, v49
	v_cvt_pk_bf16_f32 v167, v50, v51
	global_store_dwordx4 v149, v[164:167], s[14:15]
	s_nop 1
	v_add_u32_e32 v149, 0x16000, v149
	v_fmamk_f32 v150, v161, 0x3a800000, v151
	v_rsq_f32_e32 v150, v150
	s_nop 0
	v_pk_mul_f32 v[44:45], v[44:45], v[150:151] op_sel_hi:[1,0]
	v_pk_mul_f32 v[46:47], v[46:47], v[150:151] op_sel_hi:[1,0]
	v_pk_mul_f32 v[36:37], v[36:37], v[150:151] op_sel_hi:[1,0]
	v_pk_mul_f32 v[38:39], v[38:39], v[150:151] op_sel_hi:[1,0]
	v_pk_mul_f32 v[168:169], v[44:45], v[152:153]
	v_pk_mul_f32 v[170:171], v[46:47], v[152:153]
	v_exp_f32_e32 v168, v168
	v_exp_f32_e32 v169, v169
	v_exp_f32_e32 v170, v170
	v_exp_f32_e32 v171, v171
	v_pk_add_f32 v[168:169], v[168:169], v[158:159]
	v_pk_add_f32 v[170:171], v[170:171], v[158:159]
	v_rcp_f32_e32 v168, v168
	v_rcp_f32_e32 v169, v169
	v_rcp_f32_e32 v170, v170
	v_rcp_f32_e32 v171, v171
	v_pk_mul_f32 v[36:37], v[36:37], v[44:45]
	v_pk_mul_f32 v[38:39], v[38:39], v[46:47]
	v_pk_mul_f32 v[36:37], v[36:37], v[168:169]
	v_pk_mul_f32 v[38:39], v[38:39], v[170:171]
	v_pk_mul_f32 v[40:41], v[40:41], v[150:151] op_sel_hi:[1,0]
	v_pk_mul_f32 v[42:43], v[42:43], v[150:151] op_sel_hi:[1,0]
	v_pk_mul_f32 v[32:33], v[32:33], v[150:151] op_sel_hi:[1,0]
	v_pk_mul_f32 v[34:35], v[34:35], v[150:151] op_sel_hi:[1,0]
	v_pk_mul_f32 v[168:169], v[40:41], v[152:153]
	v_pk_mul_f32 v[170:171], v[42:43], v[152:153]
	v_exp_f32_e32 v168, v168
	v_exp_f32_e32 v169, v169
	v_exp_f32_e32 v170, v170
	v_exp_f32_e32 v171, v171
	v_pk_add_f32 v[168:169], v[168:169], v[158:159]
	v_pk_add_f32 v[170:171], v[170:171], v[158:159]
	v_rcp_f32_e32 v168, v168
	v_rcp_f32_e32 v169, v169
	v_rcp_f32_e32 v170, v170
	v_rcp_f32_e32 v171, v171
	v_pk_mul_f32 v[32:33], v[32:33], v[40:41]
	v_pk_mul_f32 v[34:35], v[34:35], v[42:43]
	v_pk_mul_f32 v[32:33], v[32:33], v[168:169]
	v_pk_mul_f32 v[34:35], v[34:35], v[170:171]
	v_cvt_pk_bf16_f32 v164, v36, v37
	v_cvt_pk_bf16_f32 v165, v38, v39
	v_cvt_pk_bf16_f32 v166, v32, v33
	v_cvt_pk_bf16_f32 v167, v34, v35
	global_store_dwordx4 v149, v[164:167], s[14:15]
	s_nop 1
	v_add_u32_e32 v149, 0x16000, v149
	v_fmamk_f32 v150, v162, 0x3a800000, v151
	v_rsq_f32_e32 v150, v150
	s_nop 0
	v_pk_mul_f32 v[28:29], v[28:29], v[150:151] op_sel_hi:[1,0]
	v_pk_mul_f32 v[30:31], v[30:31], v[150:151] op_sel_hi:[1,0]
	v_pk_mul_f32 v[20:21], v[20:21], v[150:151] op_sel_hi:[1,0]
	v_pk_mul_f32 v[22:23], v[22:23], v[150:151] op_sel_hi:[1,0]
	v_pk_mul_f32 v[168:169], v[28:29], v[152:153]
	v_pk_mul_f32 v[170:171], v[30:31], v[152:153]
	v_exp_f32_e32 v168, v168
	v_exp_f32_e32 v169, v169
	v_exp_f32_e32 v170, v170
	v_exp_f32_e32 v171, v171
	v_pk_add_f32 v[168:169], v[168:169], v[158:159]
	v_pk_add_f32 v[170:171], v[170:171], v[158:159]
	v_rcp_f32_e32 v168, v168
	v_rcp_f32_e32 v169, v169
	v_rcp_f32_e32 v170, v170
	v_rcp_f32_e32 v171, v171
	v_pk_mul_f32 v[20:21], v[20:21], v[28:29]
	v_pk_mul_f32 v[22:23], v[22:23], v[30:31]
	v_pk_mul_f32 v[20:21], v[20:21], v[168:169]
	v_pk_mul_f32 v[22:23], v[22:23], v[170:171]
	v_pk_mul_f32 v[24:25], v[24:25], v[150:151] op_sel_hi:[1,0]
	v_pk_mul_f32 v[26:27], v[26:27], v[150:151] op_sel_hi:[1,0]
	v_pk_mul_f32 v[16:17], v[16:17], v[150:151] op_sel_hi:[1,0]
	v_pk_mul_f32 v[18:19], v[18:19], v[150:151] op_sel_hi:[1,0]
	v_pk_mul_f32 v[168:169], v[24:25], v[152:153]
	v_pk_mul_f32 v[170:171], v[26:27], v[152:153]
	v_exp_f32_e32 v168, v168
	v_exp_f32_e32 v169, v169
	v_exp_f32_e32 v170, v170
	v_exp_f32_e32 v171, v171
	v_pk_add_f32 v[168:169], v[168:169], v[158:159]
	v_pk_add_f32 v[170:171], v[170:171], v[158:159]
	v_rcp_f32_e32 v168, v168
	v_rcp_f32_e32 v169, v169
	v_rcp_f32_e32 v170, v170
	v_rcp_f32_e32 v171, v171
	v_pk_mul_f32 v[16:17], v[16:17], v[24:25]
	v_pk_mul_f32 v[18:19], v[18:19], v[26:27]
	v_pk_mul_f32 v[16:17], v[16:17], v[168:169]
	v_pk_mul_f32 v[18:19], v[18:19], v[170:171]
	v_cvt_pk_bf16_f32 v164, v20, v21
	v_cvt_pk_bf16_f32 v165, v22, v23
	v_cvt_pk_bf16_f32 v166, v16, v17
	v_cvt_pk_bf16_f32 v167, v18, v19
	global_store_dwordx4 v149, v[164:167], s[14:15]
	s_nop 1
	v_add_u32_e32 v149, 0x16000, v149
	v_fmamk_f32 v150, v163, 0x3a800000, v151
	v_rsq_f32_e32 v150, v150
	s_nop 0
	v_pk_mul_f32 v[12:13], v[12:13], v[150:151] op_sel_hi:[1,0]
	v_pk_mul_f32 v[14:15], v[14:15], v[150:151] op_sel_hi:[1,0]
	v_pk_mul_f32 v[4:5], v[4:5], v[150:151] op_sel_hi:[1,0]
	v_pk_mul_f32 v[6:7], v[6:7], v[150:151] op_sel_hi:[1,0]
	v_pk_mul_f32 v[168:169], v[12:13], v[152:153]
	v_pk_mul_f32 v[170:171], v[14:15], v[152:153]
	v_exp_f32_e32 v168, v168
	v_exp_f32_e32 v169, v169
	v_exp_f32_e32 v170, v170
	v_exp_f32_e32 v171, v171
	v_pk_add_f32 v[168:169], v[168:169], v[158:159]
	v_pk_add_f32 v[170:171], v[170:171], v[158:159]
	v_rcp_f32_e32 v168, v168
	v_rcp_f32_e32 v169, v169
	v_rcp_f32_e32 v170, v170
	v_rcp_f32_e32 v171, v171
	v_pk_mul_f32 v[4:5], v[4:5], v[12:13]
	v_pk_mul_f32 v[6:7], v[6:7], v[14:15]
	v_pk_mul_f32 v[4:5], v[4:5], v[168:169]
	v_pk_mul_f32 v[6:7], v[6:7], v[170:171]
	v_pk_mul_f32 v[8:9], v[8:9], v[150:151] op_sel_hi:[1,0]
	v_pk_mul_f32 v[10:11], v[10:11], v[150:151] op_sel_hi:[1,0]
	v_pk_mul_f32 v[0:1], v[0:1], v[150:151] op_sel_hi:[1,0]
	v_pk_mul_f32 v[2:3], v[2:3], v[150:151] op_sel_hi:[1,0]
	v_pk_mul_f32 v[168:169], v[8:9], v[152:153]
	v_pk_mul_f32 v[170:171], v[10:11], v[152:153]
	v_exp_f32_e32 v168, v168
	v_exp_f32_e32 v169, v169
	v_exp_f32_e32 v170, v170
	v_exp_f32_e32 v171, v171
	v_pk_add_f32 v[168:169], v[168:169], v[158:159]
	v_pk_add_f32 v[170:171], v[170:171], v[158:159]
	v_rcp_f32_e32 v168, v168
	v_rcp_f32_e32 v169, v169
	v_rcp_f32_e32 v170, v170
	v_rcp_f32_e32 v171, v171
	v_pk_mul_f32 v[0:1], v[0:1], v[8:9]
	v_pk_mul_f32 v[2:3], v[2:3], v[10:11]
	v_pk_mul_f32 v[0:1], v[0:1], v[168:169]
	v_pk_mul_f32 v[2:3], v[2:3], v[170:171]
	v_cvt_pk_bf16_f32 v164, v4, v5
	v_cvt_pk_bf16_f32 v165, v6, v7
	v_cvt_pk_bf16_f32 v166, v0, v1
	v_cvt_pk_bf16_f32 v167, v2, v3
	global_store_dwordx4 v149, v[164:167], s[14:15]
